# v53 + lru_conv_own: sample-row loop unpacks deferred to one merge point (no per-tap drains), rows 14/15 of the prompt loop hoisted too
# speedup vs baseline: 1.0105x; 1.0105x over previous
; __device__ __forceinline__ void unpack8(const v4u w, float (&f)[8]) { f[0] = bf_lo(w.x); f[1] = bf_hi(w.x); f[2] = bf_lo(w.y); f[3] = bf_hi(w.y); f[4] = bf_lo(w.z); f[5] = bf_hi(w.z); f[6] = bf_lo(w.w); f[7] = bf_hi(w.w); }
; __device__ __forceinline__ v4u pack8(const float (&f)[8]) { v4u w; w.x = cvt_pk_bf16(f[0], f[1]); w.y = cvt_pk_bf16(f[2], f[3]); w.z = cvt_pk_bf16(f[4], f[5]); w.w = cvt_pk_bf16(f[6], f[7]); return w; }
; __device__ __forceinline__ void lru_conv_own(const Frame& F, CArgs* A, int j, const bf16* U, bf16* UC) {
;     ...
;         const int pm = P >> 3, hd = P & 7, c = hd * 256 + (F.tid & 31) * 8, m0 = pm * 256 + (F.tid >> 5) * 16, t0 = m0 & 4095;
;         float w[4][8], bias[8], x3[8], x2[8], x1[8];
; #pragma unroll
;         for (int k = 0; k < 4; ++k) load8f(cw + (size_t)k * 2048 + c, w[k]);
;         load8f(cb + c, bias);
;         if (t0 != 0) { unpack8(*(const v4u*)(U + (size_t)(m0 - 3) * 2048 + c), x3); unpack8(*(const v4u*)(U + (size_t)(m0 - 2) * 2048 + c), x2); unpack8(*(const v4u*)(U + (size_t)(m0 - 1) * 2048 + c), x1); }
;         else {
; #pragma unroll
;             for (int e = 0; e < 8; ++e) { x3[e] = 0.f; x2[e] = 0.f; x1[e] = 0.f; } }
; #pragma unroll
;         for (int r = 0; r < 16; ++r) { float x0[8], o[8]; unpack8(*(const v4u*)(U + (size_t)(m0 + r) * 2048 + c), x0);
; #pragma unroll
;             for (int e = 0; e < 8; ++e) o[e] = bias[e] + w[0][e] * x3[e] + w[1][e] * x2[e] + w[2][e] * x1[e] + w[3][e] * x0[e];
;             *(v4u*)(UC + (size_t)(m0 + r) * 2048 + c) = pack8(o);
;             if (t0 + r >= TSEQ - 3) store8f(A->out + O_LCP + ((size_t)(j * 2 + (m0 >> 12)) * 3 + (t0 + r - (TSEQ - 3))) * 2048 + c, x0);
; #pragma unroll
;             for (int e = 0; e < 8; ++e) { x3[e] = x2[e]; x2[e] = x1[e]; x1[e] = x0[e]; } }
;     }
.LBB0_279:
	s_or_b64 exec, exec, s[2:3]
	v_mov_b32_e32 v45, v1
	s_waitcnt vmcnt(10)
	v_lshl_add_u64 v[50:51], s[18:19], 0, v[44:45]
	v_lshlrev_b64 v[86:87], 12, v[42:43]
	v_lshl_add_u64 v[48:49], v[50:51], 0, v[86:87]
	global_load_dwordx4 v[52:55], v[48:49], off
	s_mov_b64 s[16:17], 0x1000
	v_lshl_add_u64 v[198:199], v[48:49], 0, s[16:17]
	global_load_dwordx4 v[128:131], v[198:199], off
	s_mov_b64 s[16:17], 0x2000
	v_lshl_add_u64 v[196:197], v[48:49], 0, s[16:17]
	global_load_dwordx4 v[132:135], v[196:197], off
	s_mov_b64 s[16:17], 0x3000
	v_lshl_add_u64 v[198:199], v[48:49], 0, s[16:17]
	global_load_dwordx4 v[136:139], v[198:199], off
	s_mov_b64 s[16:17], 0x4000
	v_lshl_add_u64 v[196:197], v[48:49], 0, s[16:17]
	global_load_dwordx4 v[140:143], v[196:197], off
	s_mov_b64 s[16:17], 0x5000
	v_lshl_add_u64 v[198:199], v[48:49], 0, s[16:17]
	global_load_dwordx4 v[144:147], v[198:199], off
	s_mov_b64 s[16:17], 0x6000
	v_lshl_add_u64 v[196:197], v[48:49], 0, s[16:17]
	global_load_dwordx4 v[148:151], v[196:197], off
	s_mov_b64 s[16:17], 0x7000
	v_lshl_add_u64 v[198:199], v[48:49], 0, s[16:17]
	global_load_dwordx4 v[152:155], v[198:199], off
	s_mov_b64 s[16:17], 0x8000
	v_lshl_add_u64 v[196:197], v[48:49], 0, s[16:17]
	global_load_dwordx4 v[156:159], v[196:197], off
	s_mov_b64 s[16:17], 0x9000
	v_lshl_add_u64 v[198:199], v[48:49], 0, s[16:17]
	global_load_dwordx4 v[160:163], v[198:199], off
	s_mov_b64 s[16:17], 0xa000
	v_lshl_add_u64 v[196:197], v[48:49], 0, s[16:17]
	global_load_dwordx4 v[164:167], v[196:197], off
	s_mov_b64 s[16:17], 0xb000
	v_lshl_add_u64 v[198:199], v[48:49], 0, s[16:17]
	global_load_dwordx4 v[170:173], v[198:199], off
	s_mov_b64 s[16:17], 0xc000
	v_lshl_add_u64 v[196:197], v[48:49], 0, s[16:17]
	global_load_dwordx4 v[176:179], v[196:197], off
	s_mov_b64 s[16:17], 0xd000
	v_lshl_add_u64 v[198:199], v[48:49], 0, s[16:17]
	global_load_dwordx4 v[190:193], v[198:199], off
	s_mov_b64 s[16:17], 0xe000
	v_lshl_add_u64 v[196:197], v[48:49], 0, s[16:17]
	global_load_dwordx4 v[200:203], v[196:197], off
	s_mov_b64 s[16:17], 0xf000
	v_lshl_add_u64 v[198:199], v[48:49], 0, s[16:17]
	global_load_dwordx4 v[204:207], v[198:199], off
	s_waitcnt vmcnt(25)
	v_mov_b32_e32 v56, v28
	s_waitcnt vmcnt(22)
	v_mov_b32_e32 v57, v12
	v_mov_b32_e32 v62, v107
	v_mov_b32_e32 v60, v109
	v_mov_b32_e32 v80, v103
	v_mov_b32_e32 v78, v105
	v_mov_b32_e32 v84, v99
	v_mov_b32_e32 v82, v101
	v_mov_b32_e32 v76, v91
	v_mov_b32_e32 v90, v95
	v_mov_b32_e32 v92, v97
	v_mov_b32_e32 v74, v93
	v_lshl_add_u64 v[46:47], s[46:47], 0, v[44:45]
	v_lshl_add_u64 v[86:87], v[46:47], 0, v[86:87]
	v_ashrrev_i32_e32 v44, 12, v42
	v_add_u32_e32 v44, s67, v44
	v_mul_i32_i24_e32 v44, 3, v44
	s_movk_i32 s2, 0xff0
	v_ashrrev_i32_e32 v45, 31, v44
	v_cmp_eq_u32_e32 vcc, s2, v111
	s_waitcnt vmcnt(15)
	v_lshlrev_b32_e32 v65, 16, v52
	v_and_b32_e32 v59, 0xffff0000, v52
	v_lshlrev_b32_e32 v69, 16, v53
	v_and_b32_e32 v67, 0xffff0000, v53
	v_mov_b32_e32 v52, v34
	v_mov_b32_e32 v53, v22
	v_pk_mul_f32 v[48:49], v[52:53], v[106:107]
	v_lshlrev_b32_e32 v73, 16, v54
	v_add_f32_e32 v22, v18, v48
	v_add_f32_e32 v58, v22, v49
	v_mov_b32_e32 v22, v35
	v_pk_mul_f32 v[34:35], v[22:23], v[108:109]
	v_mov_b32_e32 v49, v6
	v_add_f32_e32 v6, v19, v34
	v_mov_b32_e32 v48, v38
	v_add_f32_e32 v106, v6, v35
	v_mov_b32_e32 v6, v39
	v_mov_b32_e32 v38, v36
	v_mov_b32_e32 v39, v24
	v_pk_mul_f32 v[34:35], v[38:39], v[102:103]
	v_and_b32_e32 v71, 0xffff0000, v54
	v_add_f32_e32 v24, v20, v34
	v_add_f32_e32 v66, v24, v35
	v_mov_b32_e32 v24, v37
	v_pk_mul_f32 v[36:37], v[24:25], v[104:105]
	v_mov_b32_e32 v35, v8
	v_add_f32_e32 v8, v21, v36
	v_mov_b32_e32 v34, v40
	v_add_f32_e32 v64, v8, v37
	v_mov_b32_e32 v8, v41
	v_mov_b32_e32 v40, v26
	v_mov_b32_e32 v41, v10
	v_pk_mul_f32 v[36:37], v[40:41], v[98:99]
	v_lshlrev_b32_e32 v77, 16, v55
	v_add_f32_e32 v10, v14, v36
	v_add_f32_e32 v68, v10, v37
	v_mov_b32_e32 v10, v27
	v_pk_mul_f32 v[26:27], v[10:11], v[100:101]
	v_mov_b32_e32 v37, v2
	v_add_f32_e32 v2, v15, v26
	v_add_f32_e32 v102, v2, v27
	v_pk_mul_f32 v[26:27], v[56:57], v[94:95]
	v_and_b32_e32 v75, 0xffff0000, v55
	v_add_f32_e32 v12, v16, v26
	v_add_f32_e32 v70, v12, v27
	v_mov_b32_e32 v12, v29
	v_pk_mul_f32 v[28:29], v[52:53], v[62:63]
	v_mov_b32_e32 v54, v32
	v_add_f32_e32 v28, v18, v28
	v_add_f32_e32 v100, v28, v29
	v_pk_mul_f32 v[28:29], v[22:23], v[60:61]
	v_mov_b32_e32 v55, v4
	v_add_f32_e32 v28, v19, v28
	v_add_f32_e32 v43, v28, v29
	v_pk_mul_f32 v[28:29], v[38:39], v[80:81]
	v_pk_mul_f32 v[26:27], v[12:13], v[96:97]
	v_add_f32_e32 v28, v20, v28
	v_add_f32_e32 v80, v28, v29
	v_pk_mul_f32 v[28:29], v[24:25], v[78:79]
	v_pk_mul_f32 v[98:99], v[54:55], v[76:77]
	v_add_f32_e32 v28, v21, v28
	v_add_f32_e32 v78, v28, v29
	v_pk_mul_f32 v[28:29], v[40:41], v[84:85]
	v_add_f32_e32 v4, v17, v26
	v_add_f32_e32 v28, v14, v28
	v_add_f32_e32 v84, v28, v29
	v_pk_mul_f32 v[28:29], v[10:11], v[82:83]
	v_add_f32_e32 v60, v70, v98
	v_add_f32_e32 v28, v15, v28
	v_add_f32_e32 v82, v28, v29
	v_pk_mul_f32 v[28:29], v[56:57], v[90:91]
	v_add_f32_e32 v72, v4, v27
	v_mov_b32_e32 v4, v33
	v_add_f32_e32 v28, v16, v28
	v_add_f32_e32 v91, v60, v99
	v_pk_mul_f32 v[98:99], v[56:57], v[76:77]
	v_add_f32_e32 v94, v28, v29
	v_pk_mul_f32 v[28:29], v[12:13], v[92:93]
	v_add_f32_e32 v60, v16, v98
	v_pk_mul_f32 v[92:93], v[4:5], v[74:75]
	v_add_f32_e32 v76, v60, v99
	v_add_f32_e32 v60, v72, v92
	v_add_f32_e32 v95, v60, v93
	v_pk_mul_f32 v[92:93], v[12:13], v[74:75]
	v_mov_b32_e32 v36, v30
	v_add_f32_e32 v60, v17, v92
	v_mov_b32_e32 v72, v85
	v_add_f32_e32 v74, v60, v93
	v_pk_mul_f32 v[92:93], v[36:37], v[72:73]
	v_mov_b32_e32 v2, v31
	v_add_f32_e32 v60, v68, v92
; __device__ __forceinline__ void unpack8(const v4u w, float (&f)[8]) { f[0] = bf_lo(w.x); f[1] = bf_hi(w.x); f[2] = bf_lo(w.y); f[3] = bf_hi(w.y); f[4] = bf_lo(w.z); f[5] = bf_hi(w.z); f[6] = bf_lo(w.w); f[7] = bf_hi(w.w); }
; __device__ __forceinline__ v4u pack8(const float (&f)[8]) { v4u w; w.x = cvt_pk_bf16(f[0], f[1]); w.y = cvt_pk_bf16(f[2], f[3]); w.z = cvt_pk_bf16(f[4], f[5]); w.w = cvt_pk_bf16(f[6], f[7]); return w; }
; __device__ __forceinline__ void lru_conv_own(const Frame& F, CArgs* A, int j, const bf16* U, bf16* UC) {
;     ...
; #pragma unroll
;         for (int r = 0; r < 16; ++r) { float x0[8], o[8]; unpack8(*(const v4u*)(U + (size_t)(m0 + r) * 2048 + c), x0);
; #pragma unroll
;             for (int e = 0; e < 8; ++e) o[e] = bias[e] + w[0][e] * x3[e] + w[1][e] * x2[e] + w[2][e] * x1[e] + w[3][e] * x0[e];
;             *(v4u*)(UC + (size_t)(m0 + r) * 2048 + c) = pack8(o);
;             if (t0 + r >= TSEQ - 3) store8f(A->out + O_LCP + ((size_t)(j * 2 + (m0 >> 12)) * 3 + (t0 + r - (TSEQ - 3))) * 2048 + c, x0);
; #pragma unroll
;             for (int e = 0; e < 8; ++e) { x3[e] = x2[e]; x2[e] = x1[e]; x1[e] = x0[e]; } }
;     }
	v_add_f32_e32 v85, v60, v93
	v_pk_mul_f32 v[92:93], v[40:41], v[72:73]
	v_mov_b32_e32 v70, v83
	v_add_f32_e32 v60, v14, v92
	v_add_f32_e32 v72, v60, v93
	v_pk_mul_f32 v[92:93], v[2:3], v[70:71]
	v_mov_b32_e32 v68, v81
	v_add_f32_e32 v60, v102, v92
	v_add_f32_e32 v83, v60, v93
	v_pk_mul_f32 v[92:93], v[10:11], v[70:71]
	v_or_b32_e32 v26, 1, v42
	v_add_f32_e32 v60, v15, v92
	v_add_f32_e32 v70, v60, v93
	v_pk_mul_f32 v[92:93], v[34:35], v[68:69]
	v_ashrrev_i32_e32 v27, 31, v26
	v_add_f32_e32 v60, v66, v92
	v_add_f32_e32 v81, v60, v93
	v_pk_mul_f32 v[92:93], v[38:39], v[68:69]
	v_mov_b32_e32 v66, v79
	v_add_f32_e32 v60, v20, v92
	v_add_f32_e32 v68, v60, v93
	v_pk_mul_f32 v[92:93], v[8:9], v[66:67]
	v_lshlrev_b64 v[26:27], 12, v[26:27]
	v_add_f32_e32 v60, v64, v92
	v_mov_b32_e32 v64, v63
	v_pk_mul_f32 v[62:63], v[48:49], v[64:65]
	v_add_f32_e32 v79, v60, v93
	v_pk_mul_f32 v[92:93], v[24:25], v[66:67]
	v_add_f32_e32 v58, v58, v62
	v_add_f32_e32 v60, v21, v92
	v_add_f32_e32 v92, v58, v63
	v_pk_mul_f32 v[62:63], v[52:53], v[64:65]
	v_add_f32_e32 v113, v60, v93
	v_add_f32_e32 v58, v18, v62
	v_add_f32_e32 v66, v58, v63
	v_mov_b32_e32 v58, v61
	v_pk_mul_f32 v[60:61], v[6:7], v[58:59]
	v_lshl_add_u64 v[88:89], v[50:51], 0, v[26:27]
	v_add_f32_e32 v60, v106, v60
	v_add_f32_e32 v62, v60, v61
	v_pk_mul_f32 v[60:61], v[22:23], v[58:59]
	v_mov_b32_e32 v98, v77
	v_add_f32_e32 v58, v19, v60
	v_add_f32_e32 v64, v58, v61
	v_cvt_pk_bf16_f32 v60, v92, v62
	v_cvt_pk_bf16_f32 v61, v81, v79
	v_cvt_pk_bf16_f32 v62, v85, v83
	v_cvt_pk_bf16_f32 v63, v91, v95
	s_nop 0
	v_add_f32_e32 v28, v17, v28
	global_store_dwordx4 v[86:87], v[60:63], off
	v_add_f32_e32 v90, v28, v29
	v_mov_b32_e32 v92, v73
	v_mov_b32_e32 v88, v71
	v_lshl_add_u64 v[30:31], v[46:47], 0, v[26:27]
	v_or_b32_e32 v26, 2, v42
	v_ashrrev_i32_e32 v27, 31, v26
	v_lshlrev_b64 v[26:27], 12, v[26:27]
	v_lshl_add_u64 v[32:33], v[50:51], 0, v[26:27]
	v_or_b32_e32 v28, 3, v42
	v_ashrrev_i32_e32 v29, 31, v28
	v_lshlrev_b64 v[96:97], 12, v[28:29]
	v_lshl_add_u64 v[28:29], v[50:51], 0, v[96:97]
	v_lshl_add_u64 v[60:61], v[46:47], 0, v[96:97]
	v_or_b32_e32 v62, 4, v42
	v_ashrrev_i32_e32 v63, 31, v62
	v_lshl_add_u64 v[26:27], v[46:47], 0, v[26:27]
	s_waitcnt vmcnt(16)
	s_waitcnt vmcnt(15)
	v_lshlrev_b32_e32 v99, 16, v131
	v_pk_mul_f32 v[86:87], v[54:55], v[98:99]
	v_and_b32_e32 v95, 0xffff0000, v131
	v_add_f32_e32 v58, v94, v86
	v_add_f32_e32 v77, v58, v87
	v_pk_mul_f32 v[86:87], v[56:57], v[98:99]
	v_mov_b32_e32 v94, v75
	v_add_f32_e32 v58, v16, v86
	v_add_f32_e32 v107, v58, v87
	v_pk_mul_f32 v[86:87], v[4:5], v[94:95]
	v_lshlrev_b32_e32 v93, 16, v130
	v_add_f32_e32 v58, v90, v86
	v_add_f32_e32 v75, v58, v87
	v_pk_mul_f32 v[86:87], v[12:13], v[94:95]
	v_and_b32_e32 v89, 0xffff0000, v130
	v_add_f32_e32 v58, v17, v86
	v_add_f32_e32 v108, v58, v87
	v_pk_mul_f32 v[86:87], v[40:41], v[92:93]
	v_pk_mul_f32 v[90:91], v[36:37], v[92:93]
	v_add_f32_e32 v58, v14, v86
	v_add_f32_e32 v104, v58, v87
	v_pk_mul_f32 v[86:87], v[10:11], v[88:89]
	v_lshlrev_b32_e32 v85, 16, v129
	v_add_f32_e32 v73, v84, v90
	v_add_f32_e32 v58, v15, v86
	v_mov_b32_e32 v84, v69
	v_add_f32_e32 v73, v73, v91
	v_pk_mul_f32 v[90:91], v[2:3], v[88:89]
	v_add_f32_e32 v105, v58, v87
	v_pk_mul_f32 v[86:87], v[38:39], v[84:85]
	v_and_b32_e32 v83, 0xffff0000, v129
	v_add_f32_e32 v71, v82, v90
	v_add_f32_e32 v58, v20, v86
	v_mov_b32_e32 v82, v67
	v_add_f32_e32 v71, v71, v91
	v_pk_mul_f32 v[90:91], v[34:35], v[84:85]
	v_add_f32_e32 v106, v58, v87
	v_pk_mul_f32 v[86:87], v[24:25], v[82:83]
	v_lshlrev_b32_e32 v81, 16, v128
	v_add_f32_e32 v69, v80, v90
	v_add_f32_e32 v58, v21, v86
	v_mov_b32_e32 v80, v65
	v_add_f32_e32 v69, v69, v91
	v_pk_mul_f32 v[90:91], v[8:9], v[82:83]
	v_add_f32_e32 v112, v58, v87
	v_pk_mul_f32 v[86:87], v[52:53], v[80:81]
	v_and_b32_e32 v79, 0xffff0000, v128
	v_add_f32_e32 v67, v78, v90
	v_add_f32_e32 v58, v18, v86
	v_mov_b32_e32 v78, v59
	v_add_f32_e32 v67, v67, v91
	v_pk_mul_f32 v[90:91], v[48:49], v[80:81]
	v_add_f32_e32 v109, v58, v87
	v_pk_mul_f32 v[86:87], v[6:7], v[78:79]
	v_add_f32_e32 v65, v100, v90
	v_add_f32_e32 v43, v43, v86
	v_add_f32_e32 v65, v65, v91
	v_add_f32_e32 v43, v43, v87
	v_cvt_pk_bf16_f32 v120, v65, v43
	v_cvt_pk_bf16_f32 v121, v69, v67
	v_cvt_pk_bf16_f32 v122, v73, v71
	v_cvt_pk_bf16_f32 v123, v77, v75
	s_nop 0
	v_mov_b32_e32 v100, v99
	v_mov_b32_e32 v96, v95
	v_pk_mul_f32 v[58:59], v[22:23], v[78:79]
	v_mov_b32_e32 v90, v93
	v_mov_b32_e32 v86, v89
	v_lshlrev_b64 v[102:103], 12, v[62:63]
	v_lshl_add_u64 v[62:63], v[50:51], 0, v[102:103]
	global_store_dwordx4 v[30:31], v[120:123], off
	v_lshl_add_u64 v[30:31], v[46:47], 0, v[102:103]
	v_add_f32_e32 v58, v19, v58
	v_add_f32_e32 v92, v58, v59
	v_or_b32_e32 v32, 5, v42
	v_ashrrev_i32_e32 v33, 31, v32
	v_lshlrev_b64 v[58:59], 12, v[32:33]
	v_lshl_add_u64 v[32:33], v[50:51], 0, v[58:59]
	s_nop 0
	s_waitcnt vmcnt(15)
; __device__ __forceinline__ void unpack8(const v4u w, float (&f)[8]) { f[0] = bf_lo(w.x); f[1] = bf_hi(w.x); f[2] = bf_lo(w.y); f[3] = bf_hi(w.y); f[4] = bf_lo(w.z); f[5] = bf_hi(w.z); f[6] = bf_lo(w.w); f[7] = bf_hi(w.w); }
; __device__ __forceinline__ v4u pack8(const float (&f)[8]) { v4u w; w.x = cvt_pk_bf16(f[0], f[1]); w.y = cvt_pk_bf16(f[2], f[3]); w.z = cvt_pk_bf16(f[4], f[5]); w.w = cvt_pk_bf16(f[6], f[7]); return w; }
; __device__ __forceinline__ void lru_conv_own(const Frame& F, CArgs* A, int j, const bf16* U, bf16* UC) {
;     ...
; #pragma unroll
;         for (int r = 0; r < 16; ++r) { float x0[8], o[8]; unpack8(*(const v4u*)(U + (size_t)(m0 + r) * 2048 + c), x0);
; #pragma unroll
;             for (int e = 0; e < 8; ++e) o[e] = bias[e] + w[0][e] * x3[e] + w[1][e] * x2[e] + w[2][e] * x1[e] + w[3][e] * x0[e];
;             *(v4u*)(UC + (size_t)(m0 + r) * 2048 + c) = pack8(o);
;             if (t0 + r >= TSEQ - 3) store8f(A->out + O_LCP + ((size_t)(j * 2 + (m0 >> 12)) * 3 + (t0 + r - (TSEQ - 3))) * 2048 + c, x0);
; #pragma unroll
;             for (int e = 0; e < 8; ++e) { x3[e] = x2[e]; x2[e] = x1[e]; x1[e] = x0[e]; } }
;     }
	v_lshlrev_b32_e32 v101, 16, v135
	v_pk_mul_f32 v[98:99], v[54:55], v[100:101]
	v_and_b32_e32 v97, 0xffff0000, v135
	v_add_f32_e32 v43, v76, v98
	v_add_f32_e32 v65, v43, v99
	v_pk_mul_f32 v[98:99], v[56:57], v[100:101]
	v_pk_mul_f32 v[94:95], v[4:5], v[96:97]
	v_add_f32_e32 v43, v16, v98
	v_add_f32_e32 v80, v43, v99
	v_add_f32_e32 v43, v74, v94
	v_pk_mul_f32 v[74:75], v[12:13], v[96:97]
	v_lshlrev_b32_e32 v91, 16, v134
	v_add_f32_e32 v78, v43, v95
	v_add_f32_e32 v43, v17, v74
	v_add_f32_e32 v84, v43, v75
	v_pk_mul_f32 v[74:75], v[40:41], v[90:91]
	v_and_b32_e32 v87, 0xffff0000, v134
	v_add_f32_e32 v43, v14, v74
	v_pk_mul_f32 v[94:95], v[36:37], v[90:91]
	v_add_f32_e32 v43, v43, v75
	v_add_f32_e32 v71, v72, v94
	v_pk_mul_f32 v[74:75], v[10:11], v[86:87]
	v_pk_mul_f32 v[88:89], v[2:3], v[86:87]
	v_lshlrev_b32_e32 v77, 16, v133
	v_add_f32_e32 v82, v71, v95
	v_add_f32_e32 v71, v15, v74
	v_add_f32_e32 v70, v70, v88
	v_mov_b32_e32 v76, v85
	v_add_f32_e32 v88, v70, v89
	v_add_f32_e32 v86, v71, v75
	v_pk_mul_f32 v[70:71], v[38:39], v[76:77]
	v_and_b32_e32 v73, 0xffff0000, v133
	v_add_f32_e32 v70, v20, v70
	v_pk_mul_f32 v[74:75], v[34:35], v[76:77]
	v_mov_b32_e32 v72, v83
	v_add_f32_e32 v68, v68, v74
	v_add_f32_e32 v90, v70, v71
	v_pk_mul_f32 v[70:71], v[24:25], v[72:73]
	v_add_f32_e32 v76, v68, v75
	v_add_f32_e32 v68, v21, v70
	v_pk_mul_f32 v[74:75], v[8:9], v[72:73]
	v_lshlrev_b32_e32 v69, 16, v132
	v_add_f32_e32 v70, v113, v74
	v_add_f32_e32 v102, v68, v71
	v_mov_b32_e32 v68, v81
	v_add_f32_e32 v72, v70, v75
	v_pk_mul_f32 v[74:75], v[48:49], v[68:69]
	v_and_b32_e32 v67, 0xffff0000, v132
	v_add_f32_e32 v66, v66, v74
	v_pk_mul_f32 v[70:71], v[52:53], v[68:69]
	v_add_f32_e32 v68, v66, v75
	v_mov_b32_e32 v66, v79
	v_pk_mul_f32 v[74:75], v[6:7], v[66:67]
	v_mov_b32_e32 v98, v101
	v_add_f32_e32 v64, v64, v74
	v_add_f32_e32 v64, v64, v75
	v_cvt_pk_bf16_f32 v120, v68, v64
	v_cvt_pk_bf16_f32 v121, v76, v72
	v_cvt_pk_bf16_f32 v122, v82, v88
	v_cvt_pk_bf16_f32 v123, v65, v78
	s_nop 0
	v_mov_b32_e32 v94, v97
	v_mov_b32_e32 v88, v91
	v_add_f32_e32 v70, v18, v70
	v_add_f32_e32 v103, v70, v71
	v_pk_mul_f32 v[70:71], v[22:23], v[66:67]
	v_mov_b32_e32 v82, v87
	v_mov_b32_e32 v78, v77
	v_mov_b32_e32 v74, v73
	v_add_f32_e32 v70, v19, v70
	v_add_f32_e32 v113, v70, v71
	v_mov_b32_e32 v70, v69
	global_store_dwordx4 v[26:27], v[120:123], off
	v_or_b32_e32 v28, 6, v42
	v_ashrrev_i32_e32 v29, 31, v28
	v_lshlrev_b64 v[28:29], 12, v[28:29]
	v_lshl_add_u64 v[26:27], v[46:47], 0, v[58:59]
	v_lshl_add_u64 v[58:59], v[50:51], 0, v[28:29]
	v_lshl_add_u64 v[28:29], v[46:47], 0, v[28:29]
	s_nop 0
	s_waitcnt vmcnt(15)
	v_lshlrev_b32_e32 v99, 16, v139
	v_pk_mul_f32 v[100:101], v[54:55], v[98:99]
	v_and_b32_e32 v95, 0xffff0000, v139
	v_add_f32_e32 v64, v107, v100
	v_add_f32_e32 v81, v64, v101
	v_pk_mul_f32 v[100:101], v[56:57], v[98:99]
	v_pk_mul_f32 v[96:97], v[4:5], v[94:95]
	v_add_f32_e32 v64, v16, v100
	v_add_f32_e32 v107, v64, v101
	v_add_f32_e32 v64, v108, v96
	v_add_f32_e32 v85, v64, v97
	v_pk_mul_f32 v[96:97], v[12:13], v[94:95]
	v_lshlrev_b32_e32 v89, 16, v138
	v_add_f32_e32 v64, v17, v96
	v_add_f32_e32 v108, v64, v97
	v_pk_mul_f32 v[96:97], v[40:41], v[88:89]
	v_pk_mul_f32 v[100:101], v[36:37], v[88:89]
	v_and_b32_e32 v83, 0xffff0000, v138
	v_add_f32_e32 v64, v14, v96
	v_add_f32_e32 v66, v104, v100
	v_lshlrev_b32_e32 v79, 16, v137
	v_add_f32_e32 v91, v66, v101
	v_add_f32_e32 v66, v64, v97
	v_pk_mul_f32 v[96:97], v[10:11], v[82:83]
	v_pk_mul_f32 v[100:101], v[2:3], v[82:83]
	v_add_f32_e32 v64, v15, v96
	v_pk_mul_f32 v[76:77], v[38:39], v[78:79]
	v_and_b32_e32 v75, 0xffff0000, v137
	v_add_f32_e32 v68, v105, v100
	v_add_f32_e32 v88, v64, v97
	v_add_f32_e32 v64, v20, v76
	v_pk_mul_f32 v[96:97], v[34:35], v[78:79]
	v_add_f32_e32 v82, v68, v101
	v_add_f32_e32 v68, v106, v96
	v_add_f32_e32 v104, v64, v77
	v_pk_mul_f32 v[76:77], v[8:9], v[74:75]
	v_lshlrev_b32_e32 v71, 16, v136
	v_add_f32_e32 v78, v68, v97
	v_pk_mul_f32 v[72:73], v[24:25], v[74:75]
	v_add_f32_e32 v68, v112, v76
	v_add_f32_e32 v64, v21, v72
	v_add_f32_e32 v74, v68, v77
	v_pk_mul_f32 v[68:69], v[52:53], v[70:71]
	v_add_f32_e32 v105, v64, v73
	v_add_f32_e32 v64, v18, v68
	v_pk_mul_f32 v[72:73], v[48:49], v[70:71]
	v_and_b32_e32 v65, 0xffff0000, v136
	v_add_f32_e32 v68, v109, v72
	v_add_f32_e32 v106, v64, v69
	v_mov_b32_e32 v64, v67
	v_add_f32_e32 v70, v68, v73
	v_pk_mul_f32 v[72:73], v[6:7], v[64:65]
	v_pk_mul_f32 v[68:69], v[22:23], v[64:65]
	v_add_f32_e32 v64, v92, v72
	v_add_f32_e32 v64, v64, v73
	v_cvt_pk_bf16_f32 v120, v70, v64
	v_cvt_pk_bf16_f32 v121, v78, v74
	v_cvt_pk_bf16_f32 v122, v91, v82
	v_cvt_pk_bf16_f32 v123, v81, v85
	s_nop 0
	v_mov_b32_e32 v96, v99
	v_add_f32_e32 v67, v19, v68
	v_add_f32_e32 v114, v67, v69
	v_mov_b32_e32 v92, v95
	v_mov_b32_e32 v76, v79
	v_mov_b32_e32 v72, v75
	global_store_dwordx4 v[60:61], v[120:123], off
	v_or_b32_e32 v60, 7, v42
	v_ashrrev_i32_e32 v61, 31, v60
	v_lshlrev_b64 v[100:101], 12, v[60:61]
	v_lshl_add_u64 v[60:61], v[50:51], 0, v[100:101]
	s_nop 0
	s_waitcnt vmcnt(15)
; __device__ __forceinline__ void unpack8(const v4u w, float (&f)[8]) { f[0] = bf_lo(w.x); f[1] = bf_hi(w.x); f[2] = bf_lo(w.y); f[3] = bf_hi(w.y); f[4] = bf_lo(w.z); f[5] = bf_hi(w.z); f[6] = bf_lo(w.w); f[7] = bf_hi(w.w); }
; __device__ __forceinline__ v4u pack8(const float (&f)[8]) { v4u w; w.x = cvt_pk_bf16(f[0], f[1]); w.y = cvt_pk_bf16(f[2], f[3]); w.z = cvt_pk_bf16(f[4], f[5]); w.w = cvt_pk_bf16(f[6], f[7]); return w; }
; __device__ __forceinline__ void lru_conv_own(const Frame& F, CArgs* A, int j, const bf16* U, bf16* UC) {
;     ...
; #pragma unroll
;         for (int r = 0; r < 16; ++r) { float x0[8], o[8]; unpack8(*(const v4u*)(U + (size_t)(m0 + r) * 2048 + c), x0);
; #pragma unroll
;             for (int e = 0; e < 8; ++e) o[e] = bias[e] + w[0][e] * x3[e] + w[1][e] * x2[e] + w[2][e] * x1[e] + w[3][e] * x0[e];
;             *(v4u*)(UC + (size_t)(m0 + r) * 2048 + c) = pack8(o);
;             if (t0 + r >= TSEQ - 3) store8f(A->out + O_LCP + ((size_t)(j * 2 + (m0 >> 12)) * 3 + (t0 + r - (TSEQ - 3))) * 2048 + c, x0);
; #pragma unroll
;             for (int e = 0; e < 8; ++e) { x3[e] = x2[e]; x2[e] = x1[e]; x1[e] = x0[e]; } }
;     }
	v_lshlrev_b32_e32 v97, 16, v143
	v_pk_mul_f32 v[98:99], v[54:55], v[96:97]
	v_and_b32_e32 v93, 0xffff0000, v143
	v_add_f32_e32 v62, v80, v98
	v_add_f32_e32 v67, v62, v99
	v_pk_mul_f32 v[98:99], v[56:57], v[96:97]
	v_pk_mul_f32 v[94:95], v[4:5], v[92:93]
	v_add_f32_e32 v62, v16, v98
	v_add_f32_e32 v109, v62, v99
	v_add_f32_e32 v62, v84, v94
	v_add_f32_e32 v87, v62, v95
	v_pk_mul_f32 v[94:95], v[12:13], v[92:93]
	v_lshlrev_b32_e32 v85, 16, v142
	v_add_f32_e32 v62, v17, v94
	v_mov_b32_e32 v84, v89
	v_add_f32_e32 v112, v62, v95
	v_pk_mul_f32 v[94:95], v[40:41], v[84:85]
	v_pk_mul_f32 v[98:99], v[36:37], v[84:85]
	v_and_b32_e32 v81, 0xffff0000, v142
	v_add_f32_e32 v62, v14, v94
	v_add_f32_e32 v43, v43, v98
	v_mov_b32_e32 v80, v83
	v_lshlrev_b32_e32 v77, 16, v141
	v_add_f32_e32 v84, v43, v99
	v_add_f32_e32 v43, v62, v95
	v_pk_mul_f32 v[82:83], v[10:11], v[80:81]
	v_pk_mul_f32 v[94:95], v[2:3], v[80:81]
	v_add_f32_e32 v62, v15, v82
	v_add_f32_e32 v64, v86, v94
	v_pk_mul_f32 v[78:79], v[38:39], v[76:77]
	v_and_b32_e32 v73, 0xffff0000, v141
	v_add_f32_e32 v80, v64, v95
	v_add_f32_e32 v64, v62, v83
	v_add_f32_e32 v62, v20, v78
	v_pk_mul_f32 v[82:83], v[34:35], v[76:77]
	v_add_f32_e32 v96, v62, v79
	v_add_f32_e32 v68, v90, v82
	v_pk_mul_f32 v[78:79], v[8:9], v[72:73]
	v_add_f32_e32 v76, v68, v83
	v_add_f32_e32 v68, v102, v78
	v_lshlrev_b32_e32 v69, 16, v140
	v_pk_mul_f32 v[74:75], v[24:25], v[72:73]
	v_add_f32_e32 v72, v68, v79
	v_mov_b32_e32 v68, v71
	v_add_f32_e32 v62, v21, v74
	v_pk_mul_f32 v[70:71], v[52:53], v[68:69]
	v_add_f32_e32 v102, v62, v75
	v_add_f32_e32 v62, v18, v70
	v_pk_mul_f32 v[74:75], v[48:49], v[68:69]
	v_and_b32_e32 v63, 0xffff0000, v140
	v_add_f32_e32 v68, v103, v74
	v_add_f32_e32 v103, v62, v71
	v_mov_b32_e32 v62, v65
	v_add_f32_e32 v68, v68, v75
	v_pk_mul_f32 v[74:75], v[6:7], v[62:63]
	v_pk_mul_f32 v[70:71], v[22:23], v[62:63]
	v_add_f32_e32 v62, v113, v74
	v_add_f32_e32 v62, v62, v75
	v_cvt_pk_bf16_f32 v120, v68, v62
	v_cvt_pk_bf16_f32 v121, v76, v72
	v_cvt_pk_bf16_f32 v122, v84, v80
	v_cvt_pk_bf16_f32 v123, v67, v87
	s_nop 0
	v_mov_b32_e32 v94, v97
	global_store_dwordx4 v[30:31], v[120:123], off
	v_lshl_add_u64 v[30:31], v[46:47], 0, v[100:101]
	v_add_f32_e32 v65, v19, v70
	v_add_f32_e32 v113, v65, v71
	v_mov_b32_e32 v90, v93
	v_mov_b32_e32 v86, v85
	v_mov_b32_e32 v82, v81
	v_mov_b32_e32 v78, v77
	v_mov_b32_e32 v74, v73
	v_mov_b32_e32 v70, v69
	v_or_b32_e32 v32, 8, v42
	v_ashrrev_i32_e32 v33, 31, v32
	v_lshlrev_b64 v[98:99], 12, v[32:33]
	v_lshl_add_u64 v[32:33], v[50:51], 0, v[98:99]
	s_nop 0
	s_waitcnt vmcnt(15)
	v_lshlrev_b32_e32 v95, 16, v147
	v_pk_mul_f32 v[100:101], v[54:55], v[94:95]
	v_and_b32_e32 v91, 0xffff0000, v147
	v_add_f32_e32 v62, v107, v100
	v_add_f32_e32 v65, v62, v101
	v_pk_mul_f32 v[100:101], v[56:57], v[94:95]
	v_pk_mul_f32 v[92:93], v[4:5], v[90:91]
	v_add_f32_e32 v62, v16, v100
	v_add_f32_e32 v107, v62, v101
	v_add_f32_e32 v62, v108, v92
	v_lshlrev_b32_e32 v87, 16, v146
	v_add_f32_e32 v89, v62, v93
	v_pk_mul_f32 v[92:93], v[12:13], v[90:91]
	v_and_b32_e32 v83, 0xffff0000, v146
	v_add_f32_e32 v62, v17, v92
	v_pk_mul_f32 v[84:85], v[40:41], v[86:87]
	v_lshlrev_b32_e32 v79, 16, v145
	v_add_f32_e32 v108, v62, v93
	v_add_f32_e32 v62, v14, v84
	v_pk_mul_f32 v[92:93], v[36:37], v[86:87]
	v_pk_mul_f32 v[80:81], v[10:11], v[82:83]
	v_and_b32_e32 v75, 0xffff0000, v145
	v_add_f32_e32 v66, v66, v92
	v_add_f32_e32 v97, v62, v85
	v_add_f32_e32 v62, v15, v80
	v_pk_mul_f32 v[84:85], v[2:3], v[82:83]
	v_pk_mul_f32 v[76:77], v[38:39], v[78:79]
	v_add_f32_e32 v86, v66, v93
	v_add_f32_e32 v66, v88, v84
	v_add_f32_e32 v100, v62, v81
	v_add_f32_e32 v62, v20, v76
	v_pk_mul_f32 v[80:81], v[34:35], v[78:79]
	v_pk_mul_f32 v[72:73], v[24:25], v[74:75]
	v_lshlrev_b32_e32 v71, 16, v144
	v_add_f32_e32 v82, v66, v85
	v_add_f32_e32 v66, v104, v80
	v_add_f32_e32 v101, v62, v77
	v_add_f32_e32 v62, v21, v72
	v_pk_mul_f32 v[76:77], v[8:9], v[74:75]
	v_add_f32_e32 v78, v66, v81
	v_add_f32_e32 v66, v105, v76
	v_add_f32_e32 v104, v62, v73
	v_pk_mul_f32 v[72:73], v[48:49], v[70:71]
	v_add_f32_e32 v74, v66, v77
	v_pk_mul_f32 v[68:69], v[52:53], v[70:71]
	v_add_f32_e32 v66, v106, v72
	v_and_b32_e32 v67, 0xffff0000, v144
	v_add_f32_e32 v62, v18, v68
	v_add_f32_e32 v70, v66, v73
	v_mov_b32_e32 v66, v63
	v_add_f32_e32 v105, v62, v69
	v_pk_mul_f32 v[68:69], v[6:7], v[66:67]
	v_pk_mul_f32 v[62:63], v[22:23], v[66:67]
	v_add_f32_e32 v66, v114, v68
	v_add_f32_e32 v66, v66, v69
	v_cvt_pk_bf16_f32 v120, v70, v66
	v_cvt_pk_bf16_f32 v121, v78, v74
	v_cvt_pk_bf16_f32 v122, v86, v82
	v_cvt_pk_bf16_f32 v123, v65, v89
	s_nop 0
	v_mov_b32_e32 v92, v95
	global_store_dwordx4 v[26:27], v[120:123], off
	v_lshl_add_u64 v[26:27], v[46:47], 0, v[98:99]
	v_mov_b32_e32 v88, v91
	v_mov_b32_e32 v84, v87
	v_mov_b32_e32 v80, v83
	v_mov_b32_e32 v76, v79
	v_mov_b32_e32 v72, v75
	v_mov_b32_e32 v68, v71
	v_add_f32_e32 v62, v19, v62
	v_add_f32_e32 v106, v62, v63
	v_or_b32_e32 v58, 9, v42
	v_ashrrev_i32_e32 v59, 31, v58
	v_lshlrev_b64 v[58:59], 12, v[58:59]
	v_lshl_add_u64 v[62:63], v[50:51], 0, v[58:59]
	v_lshl_add_u64 v[58:59], v[46:47], 0, v[58:59]
	s_nop 0
	s_waitcnt vmcnt(15)
; __device__ __forceinline__ void unpack8(const v4u w, float (&f)[8]) { f[0] = bf_lo(w.x); f[1] = bf_hi(w.x); f[2] = bf_lo(w.y); f[3] = bf_hi(w.y); f[4] = bf_lo(w.z); f[5] = bf_hi(w.z); f[6] = bf_lo(w.w); f[7] = bf_hi(w.w); }
; __device__ __forceinline__ v4u pack8(const float (&f)[8]) { v4u w; w.x = cvt_pk_bf16(f[0], f[1]); w.y = cvt_pk_bf16(f[2], f[3]); w.z = cvt_pk_bf16(f[4], f[5]); w.w = cvt_pk_bf16(f[6], f[7]); return w; }
; __device__ __forceinline__ void lru_conv_own(const Frame& F, CArgs* A, int j, const bf16* U, bf16* UC) {
;     ...
; #pragma unroll
;         for (int r = 0; r < 16; ++r) { float x0[8], o[8]; unpack8(*(const v4u*)(U + (size_t)(m0 + r) * 2048 + c), x0);
; #pragma unroll
;             for (int e = 0; e < 8; ++e) o[e] = bias[e] + w[0][e] * x3[e] + w[1][e] * x2[e] + w[2][e] * x1[e] + w[3][e] * x0[e];
;             *(v4u*)(UC + (size_t)(m0 + r) * 2048 + c) = pack8(o);
;             if (t0 + r >= TSEQ - 3) store8f(A->out + O_LCP + ((size_t)(j * 2 + (m0 >> 12)) * 3 + (t0 + r - (TSEQ - 3))) * 2048 + c, x0);
; #pragma unroll
;             for (int e = 0; e < 8; ++e) { x3[e] = x2[e]; x2[e] = x1[e]; x1[e] = x0[e]; } }
;     }
	v_lshlrev_b32_e32 v93, 16, v151
	v_pk_mul_f32 v[94:95], v[54:55], v[92:93]
	v_and_b32_e32 v89, 0xffff0000, v151
	v_add_f32_e32 v66, v109, v94
	v_add_f32_e32 v99, v66, v95
	v_pk_mul_f32 v[94:95], v[56:57], v[92:93]
	v_pk_mul_f32 v[90:91], v[4:5], v[88:89]
	v_add_f32_e32 v66, v16, v94
	v_add_f32_e32 v92, v66, v95
	v_add_f32_e32 v66, v112, v90
	v_lshlrev_b32_e32 v85, 16, v150
	v_add_f32_e32 v94, v66, v91
	v_pk_mul_f32 v[90:91], v[12:13], v[88:89]
	v_pk_mul_f32 v[86:87], v[40:41], v[84:85]
	v_add_f32_e32 v66, v17, v90
	v_and_b32_e32 v81, 0xffff0000, v150
	v_add_f32_e32 v88, v66, v91
	v_add_f32_e32 v66, v14, v86
	v_lshlrev_b32_e32 v77, 16, v149
	v_pk_mul_f32 v[90:91], v[36:37], v[84:85]
	v_add_f32_e32 v84, v66, v87
	v_pk_mul_f32 v[86:87], v[2:3], v[80:81]
	v_and_b32_e32 v73, 0xffff0000, v149
	v_pk_mul_f32 v[82:83], v[10:11], v[80:81]
	v_add_f32_e32 v64, v64, v86
	v_pk_mul_f32 v[78:79], v[38:39], v[76:77]
	v_lshlrev_b32_e32 v69, 16, v148
	v_add_f32_e32 v66, v15, v82
	v_add_f32_e32 v86, v64, v87
	v_add_f32_e32 v64, v20, v78
	v_pk_mul_f32 v[74:75], v[24:25], v[72:73]
	v_add_f32_e32 v80, v66, v83
	v_pk_mul_f32 v[82:83], v[34:35], v[76:77]
	v_add_f32_e32 v76, v64, v79
	v_add_f32_e32 v64, v21, v74
	v_pk_mul_f32 v[70:71], v[52:53], v[68:69]
	v_add_f32_e32 v66, v96, v82
	v_pk_mul_f32 v[78:79], v[8:9], v[72:73]
	v_add_f32_e32 v72, v64, v75
	v_add_f32_e32 v64, v18, v70
	v_and_b32_e32 v65, 0xffff0000, v148
	v_add_f32_e32 v82, v66, v83
	v_add_f32_e32 v66, v102, v78
	v_pk_mul_f32 v[74:75], v[48:49], v[68:69]
	v_add_f32_e32 v68, v64, v71
	v_mov_b32_e32 v64, v67
	v_add_f32_e32 v78, v66, v79
	v_add_f32_e32 v66, v103, v74
	v_pk_mul_f32 v[70:71], v[6:7], v[64:65]
	v_add_f32_e32 v43, v43, v90
	v_add_f32_e32 v74, v66, v75
	v_pk_mul_f32 v[66:67], v[22:23], v[64:65]
	v_add_f32_e32 v64, v113, v70
	v_add_f32_e32 v43, v43, v91
	v_add_f32_e32 v64, v64, v71
	v_cvt_pk_bf16_f32 v112, v74, v64
	v_cvt_pk_bf16_f32 v113, v82, v78
	v_cvt_pk_bf16_f32 v114, v43, v86
	v_cvt_pk_bf16_f32 v115, v99, v94
	s_nop 0
	v_mov_b32_e32 v90, v93
	global_store_dwordx4 v[28:29], v[112:115], off
	v_mov_b32_e32 v86, v85
	v_mov_b32_e32 v82, v81
	v_mov_b32_e32 v78, v77
	v_mov_b32_e32 v74, v73
	v_mov_b32_e32 v70, v69
	v_add_f32_e32 v66, v19, v66
	v_add_f32_e32 v98, v66, v67
	v_mov_b32_e32 v66, v65
	v_or_b32_e32 v60, 10, v42
	v_ashrrev_i32_e32 v61, 31, v60
	v_lshlrev_b64 v[94:95], 12, v[60:61]
	v_lshl_add_u64 v[60:61], v[50:51], 0, v[94:95]
	s_nop 0
	s_waitcnt vmcnt(15)
	v_lshlrev_b32_e32 v91, 16, v155
	v_pk_mul_f32 v[102:103], v[54:55], v[90:91]
	v_and_b32_e32 v29, 0xffff0000, v155
	v_add_f32_e32 v28, v107, v102
	v_add_f32_e32 v93, v28, v103
	v_pk_mul_f32 v[102:103], v[56:57], v[90:91]
	v_lshlrev_b32_e32 v87, 16, v154
	v_add_f32_e32 v28, v16, v102
	v_add_f32_e32 v43, v28, v103
	v_mov_b32_e32 v28, v89
	v_pk_mul_f32 v[102:103], v[4:5], v[28:29]
	v_and_b32_e32 v83, 0xffff0000, v154
	v_add_f32_e32 v64, v108, v102
	v_add_f32_e32 v89, v64, v103
	v_pk_mul_f32 v[102:103], v[12:13], v[28:29]
	v_pk_mul_f32 v[108:109], v[36:37], v[86:87]
	v_add_f32_e32 v28, v17, v102
	v_add_f32_e32 v90, v28, v103
	v_pk_mul_f32 v[102:103], v[40:41], v[86:87]
	v_add_f32_e32 v64, v97, v108
	v_add_f32_e32 v28, v14, v102
	v_pk_mul_f32 v[96:97], v[10:11], v[82:83]
	v_lshlrev_b32_e32 v79, 16, v153
	v_add_f32_e32 v86, v28, v103
	v_add_f32_e32 v28, v15, v96
	v_pk_mul_f32 v[102:103], v[2:3], v[82:83]
	v_add_f32_e32 v85, v64, v109
	v_add_f32_e32 v64, v100, v102
	v_add_f32_e32 v82, v28, v97
	v_pk_mul_f32 v[96:97], v[38:39], v[78:79]
	v_and_b32_e32 v75, 0xffff0000, v153
	v_add_f32_e32 v81, v64, v103
	v_add_f32_e32 v28, v20, v96
	v_pk_mul_f32 v[102:103], v[34:35], v[78:79]
	v_add_f32_e32 v78, v28, v97
	v_add_f32_e32 v64, v101, v102
	v_pk_mul_f32 v[96:97], v[24:25], v[74:75]
	v_pk_mul_f32 v[100:101], v[8:9], v[74:75]
	v_lshlrev_b32_e32 v71, 16, v152
	v_add_f32_e32 v77, v64, v103
	v_add_f32_e32 v28, v21, v96
	v_add_f32_e32 v64, v104, v100
	v_add_f32_e32 v73, v64, v101
	v_add_f32_e32 v74, v28, v97
	v_pk_mul_f32 v[96:97], v[52:53], v[70:71]
	v_pk_mul_f32 v[100:101], v[48:49], v[70:71]
	v_and_b32_e32 v67, 0xffff0000, v152
	v_add_f32_e32 v28, v18, v96
	v_add_f32_e32 v64, v105, v100
	v_add_f32_e32 v69, v64, v101
	v_add_f32_e32 v70, v28, v97
	v_pk_mul_f32 v[64:65], v[22:23], v[66:67]
	v_pk_mul_f32 v[96:97], v[6:7], v[66:67]
	v_add_f32_e32 v28, v19, v64
	v_add_f32_e32 v64, v106, v96
	v_add_f32_e32 v64, v64, v97
	v_cvt_pk_bf16_f32 v104, v69, v64
	v_cvt_pk_bf16_f32 v105, v77, v73
	v_cvt_pk_bf16_f32 v106, v85, v81
	v_cvt_pk_bf16_f32 v107, v93, v89
	s_nop 0
	v_mov_b32_e32 v96, v91
	v_lshl_add_u64 v[32:33], v[46:47], 0, v[94:95]
	v_add_f32_e32 v103, v28, v65
	global_store_dwordx4 v[30:31], v[104:107], off
	v_or_b32_e32 v30, 11, v42
	v_ashrrev_i32_e32 v31, 31, v30
	v_lshlrev_b64 v[30:31], 12, v[30:31]
	v_lshl_add_u64 v[64:65], v[50:51], 0, v[30:31]
	s_nop 0
	s_waitcnt vmcnt(15)
; __device__ __forceinline__ void unpack8(const v4u w, float (&f)[8]) { f[0] = bf_lo(w.x); f[1] = bf_hi(w.x); f[2] = bf_lo(w.y); f[3] = bf_hi(w.y); f[4] = bf_lo(w.z); f[5] = bf_hi(w.z); f[6] = bf_lo(w.w); f[7] = bf_hi(w.w); }
; __device__ __forceinline__ v4u pack8(const float (&f)[8]) { v4u w; w.x = cvt_pk_bf16(f[0], f[1]); w.y = cvt_pk_bf16(f[2], f[3]); w.z = cvt_pk_bf16(f[4], f[5]); w.w = cvt_pk_bf16(f[6], f[7]); return w; }
; __device__ __forceinline__ void lru_conv_own(const Frame& F, CArgs* A, int j, const bf16* U, bf16* UC) {
;     ...
; #pragma unroll
;         for (int r = 0; r < 16; ++r) { float x0[8], o[8]; unpack8(*(const v4u*)(U + (size_t)(m0 + r) * 2048 + c), x0);
; #pragma unroll
;             for (int e = 0; e < 8; ++e) o[e] = bias[e] + w[0][e] * x3[e] + w[1][e] * x2[e] + w[2][e] * x1[e] + w[3][e] * x0[e];
;             *(v4u*)(UC + (size_t)(m0 + r) * 2048 + c) = pack8(o);
;             if (t0 + r >= TSEQ - 3) store8f(A->out + O_LCP + ((size_t)(j * 2 + (m0 >> 12)) * 3 + (t0 + r - (TSEQ - 3))) * 2048 + c, x0);
; #pragma unroll
;             for (int e = 0; e < 8; ++e) { x3[e] = x2[e]; x2[e] = x1[e]; x1[e] = x0[e]; } }
;     }
	v_lshlrev_b32_e32 v97, 16, v159
	v_pk_mul_f32 v[94:95], v[54:55], v[96:97]
	v_and_b32_e32 v93, 0xffff0000, v159
	v_add_f32_e32 v28, v92, v94
	v_add_f32_e32 v91, v28, v95
	v_pk_mul_f32 v[94:95], v[56:57], v[96:97]
	v_mov_b32_e32 v92, v29
	v_add_f32_e32 v28, v16, v94
	v_add_f32_e32 v96, v28, v95
	v_pk_mul_f32 v[28:29], v[4:5], v[92:93]
	v_lshlrev_b32_e32 v89, 16, v158
	v_add_f32_e32 v28, v88, v28
	v_mov_b32_e32 v88, v87
	v_pk_mul_f32 v[94:95], v[36:37], v[88:89]
	v_and_b32_e32 v85, 0xffff0000, v158
	v_add_f32_e32 v66, v84, v94
	v_mov_b32_e32 v84, v83
	v_add_f32_e32 v87, v66, v95
	v_pk_mul_f32 v[94:95], v[2:3], v[84:85]
	v_lshlrev_b32_e32 v81, 16, v157
	v_add_f32_e32 v66, v80, v94
	v_mov_b32_e32 v80, v79
	v_add_f32_e32 v83, v66, v95
	v_pk_mul_f32 v[94:95], v[34:35], v[80:81]
	v_and_b32_e32 v77, 0xffff0000, v157
	v_add_f32_e32 v66, v76, v94
	v_mov_b32_e32 v76, v75
	v_add_f32_e32 v79, v66, v95
	v_pk_mul_f32 v[94:95], v[8:9], v[76:77]
	v_lshlrev_b32_e32 v73, 16, v156
	v_add_f32_e32 v66, v72, v94
	v_mov_b32_e32 v72, v71
	v_add_f32_e32 v75, v66, v95
	v_pk_mul_f32 v[94:95], v[48:49], v[72:73]
	v_and_b32_e32 v69, 0xffff0000, v156
	v_add_f32_e32 v66, v68, v94
	v_mov_b32_e32 v68, v67
	v_add_f32_e32 v71, v66, v95
	v_pk_mul_f32 v[66:67], v[6:7], v[68:69]
	v_add_f32_e32 v99, v28, v29
	v_add_f32_e32 v66, v98, v66
	v_add_f32_e32 v66, v66, v67
	v_cvt_pk_bf16_f32 v106, v71, v66
	v_cvt_pk_bf16_f32 v107, v79, v75
	v_cvt_pk_bf16_f32 v108, v87, v83
	v_cvt_pk_bf16_f32 v109, v91, v99
	s_nop 0
	v_pk_mul_f32 v[28:29], v[12:13], v[92:93]
	v_mov_b32_e32 v98, v97
	v_add_f32_e32 v28, v17, v28
	v_add_f32_e32 v92, v28, v29
	v_pk_mul_f32 v[28:29], v[40:41], v[88:89]
	global_store_dwordx4 v[26:27], v[106:109], off
	v_add_f32_e32 v28, v14, v28
	v_add_f32_e32 v88, v28, v29
	v_pk_mul_f32 v[28:29], v[10:11], v[84:85]
	v_mov_b32_e32 v94, v93
	v_add_f32_e32 v28, v15, v28
	v_add_f32_e32 v84, v28, v29
	v_pk_mul_f32 v[28:29], v[38:39], v[80:81]
	v_or_b32_e32 v26, 12, v42
	v_add_f32_e32 v28, v20, v28
	v_add_f32_e32 v80, v28, v29
	v_pk_mul_f32 v[28:29], v[24:25], v[76:77]
	v_ashrrev_i32_e32 v27, 31, v26
	v_add_f32_e32 v28, v21, v28
	v_add_f32_e32 v101, v28, v29
	v_pk_mul_f32 v[28:29], v[52:53], v[72:73]
	v_lshlrev_b64 v[26:27], 12, v[26:27]
	v_add_f32_e32 v28, v18, v28
	v_add_f32_e32 v102, v28, v29
	v_pk_mul_f32 v[28:29], v[22:23], v[68:69]
	v_lshl_add_u64 v[66:67], v[50:51], 0, v[26:27]
	v_add_f32_e32 v28, v19, v28
	v_add_f32_e32 v105, v28, v29
	v_lshl_add_u64 v[62:63], v[46:47], 0, v[30:31]
	v_lshl_add_u64 v[28:29], v[46:47], 0, v[26:27]
	v_or_b32_e32 v26, 13, v42
	v_ashrrev_i32_e32 v27, 31, v26
	v_lshlrev_b64 v[26:27], 12, v[26:27]
	v_lshl_add_u64 v[30:31], v[50:51], 0, v[26:27]
	v_lshl_add_u64 v[26:27], v[46:47], 0, v[26:27]
	s_nop 0
	s_waitcnt vmcnt(15)
	v_lshlrev_b32_e32 v99, 16, v163
	v_pk_mul_f32 v[106:107], v[54:55], v[98:99]
	v_and_b32_e32 v95, 0xffff0000, v163
	v_add_f32_e32 v43, v43, v106
	v_add_f32_e32 v97, v43, v107
	v_pk_mul_f32 v[106:107], v[56:57], v[98:99]
	v_lshlrev_b32_e32 v91, 16, v162
	v_add_f32_e32 v43, v16, v106
	v_add_f32_e32 v100, v43, v107
	v_pk_mul_f32 v[106:107], v[4:5], v[94:95]
	v_and_b32_e32 v87, 0xffff0000, v162
	v_add_f32_e32 v43, v90, v106
	v_add_f32_e32 v93, v43, v107
	v_pk_mul_f32 v[106:107], v[12:13], v[94:95]
	v_mov_b32_e32 v90, v89
	v_add_f32_e32 v43, v17, v106
	v_add_f32_e32 v43, v43, v107
	v_pk_mul_f32 v[106:107], v[40:41], v[90:91]
	v_pk_mul_f32 v[108:109], v[36:37], v[90:91]
	v_add_f32_e32 v68, v14, v106
	v_add_f32_e32 v72, v86, v108
	v_mov_b32_e32 v86, v85
	v_add_f32_e32 v89, v72, v109
	v_add_f32_e32 v98, v68, v107
	v_pk_mul_f32 v[106:107], v[10:11], v[86:87]
	v_pk_mul_f32 v[108:109], v[2:3], v[86:87]
	v_lshlrev_b32_e32 v83, 16, v161
	v_add_f32_e32 v68, v15, v106
	v_add_f32_e32 v72, v82, v108
	v_mov_b32_e32 v82, v81
	v_add_f32_e32 v85, v72, v109
	v_add_f32_e32 v86, v68, v107
	v_pk_mul_f32 v[106:107], v[38:39], v[82:83]
	v_pk_mul_f32 v[108:109], v[34:35], v[82:83]
	v_and_b32_e32 v79, 0xffff0000, v161
	v_add_f32_e32 v68, v20, v106
	v_add_f32_e32 v72, v78, v108
	v_mov_b32_e32 v78, v77
	v_add_f32_e32 v104, v68, v107
	v_pk_mul_f32 v[76:77], v[24:25], v[78:79]
	v_pk_mul_f32 v[106:107], v[8:9], v[78:79]
	v_lshlrev_b32_e32 v75, 16, v160
	v_add_f32_e32 v81, v72, v109
	v_add_f32_e32 v68, v21, v76
	v_add_f32_e32 v72, v74, v106
	v_mov_b32_e32 v74, v73
	v_add_f32_e32 v106, v68, v77
	v_pk_mul_f32 v[76:77], v[48:49], v[74:75]
	v_add_f32_e32 v78, v72, v107
	v_pk_mul_f32 v[72:73], v[52:53], v[74:75]
	v_add_f32_e32 v70, v70, v76
	v_and_b32_e32 v71, 0xffff0000, v160
	v_add_f32_e32 v68, v18, v72
	v_add_f32_e32 v74, v70, v77
	v_mov_b32_e32 v70, v69
	v_add_f32_e32 v107, v68, v73
	v_pk_mul_f32 v[72:73], v[6:7], v[70:71]
	v_pk_mul_f32 v[68:69], v[22:23], v[70:71]
	v_add_f32_e32 v70, v103, v72
	v_add_f32_e32 v70, v70, v73
	v_cvt_pk_bf16_f32 v112, v74, v70
	v_cvt_pk_bf16_f32 v113, v81, v78
	v_cvt_pk_bf16_f32 v114, v89, v85
	v_cvt_pk_bf16_f32 v115, v97, v93
	s_nop 0
	v_add_f32_e32 v68, v19, v68
	global_store_dwordx4 v[58:59], v[112:115], off
	v_mov_b32_e32 v58, v99
	v_add_f32_e32 v109, v68, v69
	v_mov_b32_e32 v72, v87
	v_mov_b32_e32 v76, v83
	s_nop 0
	s_waitcnt vmcnt(15)
; __device__ __forceinline__ void unpack8(const v4u w, float (&f)[8]) { f[0] = bf_lo(w.x); f[1] = bf_hi(w.x); f[2] = bf_lo(w.y); f[3] = bf_hi(w.y); f[4] = bf_lo(w.z); f[5] = bf_hi(w.z); f[6] = bf_lo(w.w); f[7] = bf_hi(w.w); }
; __device__ __forceinline__ v4u pack8(const float (&f)[8]) { v4u w; w.x = cvt_pk_bf16(f[0], f[1]); w.y = cvt_pk_bf16(f[2], f[3]); w.z = cvt_pk_bf16(f[4], f[5]); w.w = cvt_pk_bf16(f[6], f[7]); return w; }
; __device__ __forceinline__ void lru_conv_own(const Frame& F, CArgs* A, int j, const bf16* U, bf16* UC) {
;     ...
; #pragma unroll
;         for (int r = 0; r < 16; ++r) { float x0[8], o[8]; unpack8(*(const v4u*)(U + (size_t)(m0 + r) * 2048 + c), x0);
; #pragma unroll
;             for (int e = 0; e < 8; ++e) o[e] = bias[e] + w[0][e] * x3[e] + w[1][e] * x2[e] + w[2][e] * x1[e] + w[3][e] * x0[e];
;             *(v4u*)(UC + (size_t)(m0 + r) * 2048 + c) = pack8(o);
;             if (t0 + r >= TSEQ - 3) store8f(A->out + O_LCP + ((size_t)(j * 2 + (m0 >> 12)) * 3 + (t0 + r - (TSEQ - 3))) * 2048 + c, x0);
; #pragma unroll
;             for (int e = 0; e < 8; ++e) { x3[e] = x2[e]; x2[e] = x1[e]; x1[e] = x0[e]; } }
;     }
	v_lshlrev_b32_e32 v59, 16, v167
	v_pk_mul_f32 v[112:113], v[56:57], v[58:59]
	v_pk_mul_f32 v[114:115], v[54:55], v[58:59]
	v_add_f32_e32 v60, v16, v112
	v_add_f32_e32 v58, v96, v114
	v_and_b32_e32 v61, 0xffff0000, v167
	v_add_f32_e32 v115, v58, v115
	v_add_f32_e32 v58, v60, v113
	v_mov_b32_e32 v60, v95
	v_pk_mul_f32 v[94:95], v[12:13], v[60:61]
	v_lshlrev_b32_e32 v69, 16, v166
	v_add_f32_e32 v68, v17, v94
	v_pk_mul_f32 v[96:97], v[4:5], v[60:61]
	v_add_f32_e32 v99, v68, v95
	v_mov_b32_e32 v68, v91
	v_add_f32_e32 v60, v92, v96
	v_pk_mul_f32 v[90:91], v[40:41], v[68:69]
	v_pk_mul_f32 v[92:93], v[36:37], v[68:69]
	v_and_b32_e32 v73, 0xffff0000, v166
	v_add_f32_e32 v70, v14, v90
	v_add_f32_e32 v68, v88, v92
	v_add_f32_e32 v94, v68, v93
	v_add_f32_e32 v68, v70, v91
	v_pk_mul_f32 v[90:91], v[10:11], v[72:73]
	v_lshlrev_b32_e32 v77, 16, v165
	v_add_f32_e32 v70, v15, v90
	v_add_f32_e32 v103, v70, v91
	v_pk_mul_f32 v[82:83], v[38:39], v[76:77]
	v_pk_mul_f32 v[90:91], v[34:35], v[76:77]
	v_and_b32_e32 v81, 0xffff0000, v165
	v_add_f32_e32 v70, v20, v82
	v_add_f32_e32 v74, v80, v90
	v_mov_b32_e32 v80, v79
	v_pk_mul_f32 v[92:93], v[2:3], v[72:73]
	v_add_f32_e32 v108, v70, v83
	v_pk_mul_f32 v[78:79], v[24:25], v[80:81]
	v_pk_mul_f32 v[82:83], v[8:9], v[80:81]
	v_lshlrev_b32_e32 v85, 16, v164
	v_add_f32_e32 v72, v84, v92
	v_add_f32_e32 v76, v74, v91
	v_add_f32_e32 v70, v21, v78
	v_add_f32_e32 v74, v101, v82
	v_mov_b32_e32 v84, v75
	v_add_f32_e32 v80, v74, v83
	v_add_f32_e32 v101, v70, v79
	v_pk_mul_f32 v[74:75], v[52:53], v[84:85]
	v_pk_mul_f32 v[78:79], v[48:49], v[84:85]
	v_and_b32_e32 v89, 0xffff0000, v164
	v_add_f32_e32 v70, v18, v74
	v_add_f32_e32 v74, v102, v78
	v_mov_b32_e32 v88, v71
	v_add_f32_e32 v78, v74, v79
	v_add_f32_e32 v102, v70, v75
	v_pk_mul_f32 v[74:75], v[6:7], v[88:89]
	v_add_f32_e32 v60, v60, v97
	v_add_f32_e32 v74, v105, v74
	v_add_f32_e32 v72, v72, v93
	v_add_f32_e32 v74, v74, v75
	v_cvt_pk_bf16_f32 v112, v78, v74
	v_cvt_pk_bf16_f32 v113, v76, v80
	v_cvt_pk_bf16_f32 v114, v94, v72
	v_cvt_pk_bf16_f32 v115, v115, v60
	s_nop 0
	v_mov_b32_e32 v74, v85
	v_mov_b32_e32 v84, v61
	v_mov_b32_e32 v82, v73
	v_mov_b32_e32 v72, v69
	global_store_dwordx4 v[32:33], v[112:115], off
	v_mov_b32_e32 v32, v59
	v_mov_b32_e32 v78, v81
	v_mov_b32_e32 v80, v77
	v_pk_mul_f32 v[70:71], v[22:23], v[88:89]
	s_nop 0
	s_waitcnt vmcnt(15)
	v_and_b32_e32 v85, 0xffff0000, v173
	v_pk_mul_f32 v[60:61], v[4:5], v[84:85]
	v_lshlrev_b32_e32 v73, 16, v172
	v_add_f32_e32 v43, v43, v60
	v_lshlrev_b32_e32 v33, 16, v173
	v_add_f32_e32 v43, v43, v61
	v_pk_mul_f32 v[60:61], v[36:37], v[72:73]
	v_and_b32_e32 v83, 0xffff0000, v172
	v_pk_mul_f32 v[64:65], v[54:55], v[32:33]
	v_add_f32_e32 v60, v98, v60
	v_add_f32_e32 v59, v100, v64
	v_add_f32_e32 v64, v60, v61
	v_pk_mul_f32 v[60:61], v[2:3], v[82:83]
	v_lshlrev_b32_e32 v81, 16, v171
	v_add_f32_e32 v60, v86, v60
	v_add_f32_e32 v59, v59, v65
	v_add_f32_e32 v65, v60, v61
	v_pk_mul_f32 v[60:61], v[34:35], v[80:81]
	v_and_b32_e32 v79, 0xffff0000, v171
	v_add_f32_e32 v60, v104, v60
	v_add_f32_e32 v69, v60, v61
	v_pk_mul_f32 v[60:61], v[8:9], v[78:79]
	v_lshlrev_b32_e32 v75, 16, v170
	v_add_f32_e32 v60, v106, v60
	v_add_f32_e32 v70, v19, v70
	v_pk_mul_f32 v[126:127], v[40:41], v[72:73]
	v_add_f32_e32 v72, v60, v61
	v_pk_mul_f32 v[60:61], v[48:49], v[74:75]
	v_add_f32_e32 v105, v70, v71
	v_and_b32_e32 v71, 0xffff0000, v170
	v_mov_b32_e32 v70, v89
	v_add_f32_e32 v60, v107, v60
	v_pk_mul_f32 v[92:93], v[52:53], v[74:75]
	v_add_f32_e32 v74, v60, v61
	v_pk_mul_f32 v[60:61], v[6:7], v[70:71]
	v_pk_mul_f32 v[90:91], v[22:23], v[70:71]
	v_add_f32_e32 v60, v109, v60
	v_add_f32_e32 v60, v60, v61
	v_cvt_pk_bf16_f32 v112, v74, v60
	v_cvt_pk_bf16_f32 v113, v69, v72
	v_cvt_pk_bf16_f32 v114, v64, v65
	v_cvt_pk_bf16_f32 v115, v59, v43
	s_nop 0
	v_mov_b32_e32 v60, v33
	global_store_dwordx4 v[62:63], v[112:115], off
	v_pk_mul_f32 v[62:63], v[56:57], v[32:33]
	v_mov_b32_e32 v66, v73
	v_add_f32_e32 v32, v16, v62
	v_add_f32_e32 v62, v32, v63
	v_mov_b32_e32 v64, v83
	v_add_f32_e32 v76, v19, v90
	v_add_f32_e32 v70, v76, v91
	v_mov_b32_e32 v76, v81
	v_pk_mul_f32 v[96:97], v[38:39], v[80:81]
	v_add_f32_e32 v88, v18, v92
	v_add_f32_e32 v43, v88, v93
	v_mov_b32_e32 v88, v75
	v_pk_mul_f32 v[94:95], v[24:25], v[78:79]
	v_mov_b32_e32 v86, v71
	v_add_f32_e32 v90, v21, v94
	v_add_f32_e32 v92, v20, v96
	v_add_f32_e32 v72, v92, v97
	v_add_f32_e32 v78, v90, v95
	v_pk_mul_f32 v[124:125], v[10:11], v[82:83]
	v_add_f32_e32 v96, v14, v126
	v_add_f32_e32 v94, v15, v124
	v_add_f32_e32 v106, v94, v125
	v_add_f32_e32 v104, v96, v127
	s_nop 0
	s_waitcnt vmcnt(15)
	v_lshlrev_b32_e32 v61, 16, v179
	v_pk_mul_f32 v[32:33], v[54:55], v[60:61]
	v_and_b32_e32 v59, 0xffff0000, v179
	v_add_f32_e32 v32, v58, v32
	v_add_f32_e32 v63, v32, v33
	v_pk_mul_f32 v[32:33], v[12:13], v[84:85]
	v_mov_b32_e32 v58, v85
	v_add_f32_e32 v32, v17, v32
	v_add_f32_e32 v107, v32, v33
	v_pk_mul_f32 v[32:33], v[4:5], v[58:59]
	v_lshlrev_b32_e32 v67, 16, v178
	v_add_f32_e32 v32, v99, v32
	v_add_f32_e32 v74, v32, v33
	v_pk_mul_f32 v[32:33], v[36:37], v[66:67]
	v_and_b32_e32 v65, 0xffff0000, v178
	v_add_f32_e32 v32, v68, v32
	v_add_f32_e32 v73, v32, v33
	v_pk_mul_f32 v[32:33], v[2:3], v[64:65]
	v_lshlrev_b32_e32 v77, 16, v177
	v_add_f32_e32 v32, v103, v32
	v_add_f32_e32 v80, v32, v33
	v_pk_mul_f32 v[32:33], v[34:35], v[76:77]
	v_and_b32_e32 v69, 0xffff0000, v177
	v_add_f32_e32 v32, v108, v32
	v_mov_b32_e32 v68, v79
	v_add_f32_e32 v81, v32, v33
	v_pk_mul_f32 v[32:33], v[8:9], v[68:69]
	v_lshlrev_b32_e32 v89, 16, v176
	v_add_f32_e32 v32, v101, v32
	v_add_f32_e32 v79, v32, v33
	v_pk_mul_f32 v[32:33], v[48:49], v[88:89]
	v_and_b32_e32 v87, 0xffff0000, v176
	v_add_f32_e32 v32, v102, v32
	v_add_f32_e32 v75, v32, v33
	v_pk_mul_f32 v[32:33], v[6:7], v[86:87]
	v_mov_b32_e32 v82, v77
	v_add_f32_e32 v32, v105, v32
	v_add_f32_e32 v32, v32, v33
	v_cvt_pk_bf16_f32 v90, v75, v32
	v_cvt_pk_bf16_f32 v91, v81, v79
	v_cvt_pk_bf16_f32 v92, v73, v80
	v_cvt_pk_bf16_f32 v93, v63, v74
	s_nop 0
	v_mov_b32_e32 v80, v87
	v_mov_b32_e32 v84, v89
	v_mov_b32_e32 v74, v69
	global_store_dwordx4 v[28:29], v[90:93], off
	s_nop 0
	s_waitcnt vmcnt(15)
; __device__ __forceinline__ void unpack8(const v4u w, float (&f)[8]) { f[0] = bf_lo(w.x); f[1] = bf_hi(w.x); f[2] = bf_lo(w.y); f[3] = bf_hi(w.y); f[4] = bf_lo(w.z); f[5] = bf_hi(w.z); f[6] = bf_lo(w.w); f[7] = bf_hi(w.w); }
; __device__ __forceinline__ v4u pack8(const float (&f)[8]) { v4u w; w.x = cvt_pk_bf16(f[0], f[1]); w.y = cvt_pk_bf16(f[2], f[3]); w.z = cvt_pk_bf16(f[4], f[5]); w.w = cvt_pk_bf16(f[6], f[7]); return w; }
; __device__ __forceinline__ void lru_conv_own(const Frame& F, CArgs* A, int j, const bf16* U, bf16* UC) {
;     ...
; #pragma unroll
;         for (int r = 0; r < 16; ++r) { float x0[8], o[8]; unpack8(*(const v4u*)(U + (size_t)(m0 + r) * 2048 + c), x0);
; #pragma unroll
;             for (int e = 0; e < 8; ++e) o[e] = bias[e] + w[0][e] * x3[e] + w[1][e] * x2[e] + w[2][e] * x1[e] + w[3][e] * x0[e];
;             *(v4u*)(UC + (size_t)(m0 + r) * 2048 + c) = pack8(o);
;             if (t0 + r >= TSEQ - 3) store8f(A->out + O_LCP + ((size_t)(j * 2 + (m0 >> 12)) * 3 + (t0 + r - (TSEQ - 3))) * 2048 + c, x0);
; #pragma unroll
;             for (int e = 0; e < 8; ++e) { x3[e] = x2[e]; x2[e] = x1[e]; x1[e] = x0[e]; } }
;     }
	v_and_b32_e32 v81, 0xffff0000, v190
	v_pk_mul_f32 v[94:95], v[6:7], v[80:81]
	v_lshlrev_b32_e32 v83, 16, v191
	v_add_f32_e32 v94, v70, v94
	v_and_b32_e32 v71, 0xffff0000, v192
	v_mov_b32_e32 v70, v65
	v_lshlrev_b32_e32 v85, 16, v190
	v_and_b32_e32 v75, 0xffff0000, v191
	v_pk_mul_f32 v[30:31], v[34:35], v[82:83]
	v_pk_mul_f32 v[100:101], v[2:3], v[70:71]
	v_add_f32_e32 v30, v72, v30
	v_add_f32_e32 v72, v106, v100
	v_lshlrev_b32_e32 v73, 16, v193
	v_add_f32_e32 v90, v72, v101
	v_mov_b32_e32 v72, v61
	v_pk_mul_f32 v[96:97], v[48:49], v[84:85]
	v_pk_mul_f32 v[98:99], v[8:9], v[74:75]
	v_pk_mul_f32 v[28:29], v[54:55], v[72:73]
	v_add_f32_e32 v43, v43, v96
	v_add_f32_e32 v96, v78, v98
	v_lshlrev_b32_e32 v79, 16, v192
	v_mov_b32_e32 v78, v67
	v_and_b32_e32 v63, 0xffff0000, v193
	v_add_f32_e32 v28, v62, v28
	v_mov_b32_e32 v62, v59
	v_pk_mul_f32 v[102:103], v[36:37], v[78:79]
	v_add_f32_e32 v91, v28, v29
	v_pk_mul_f32 v[28:29], v[4:5], v[62:63]
	v_add_f32_e32 v32, v104, v102
	v_add_f32_e32 v30, v30, v31
	v_add_f32_e32 v31, v96, v99
	v_add_f32_e32 v28, v107, v28
	v_add_f32_e32 v33, v43, v97
	v_add_f32_e32 v43, v94, v95
	v_add_f32_e32 v32, v32, v103
	v_add_f32_e32 v92, v28, v29
	v_cvt_pk_bf16_f32 v28, v33, v43
	v_cvt_pk_bf16_f32 v29, v30, v31
	v_cvt_pk_bf16_f32 v30, v32, v90
	v_cvt_pk_bf16_f32 v31, v91, v92
	global_store_dwordx4 v[26:27], v[28:31], off
	s_and_saveexec_b64 s[2:3], vcc
	s_cbranch_execz .LBB0_281
	s_load_dwordx2 s[16:17], s[0:1], 0xe0
	v_lshlrev_b64 v[30:31], 13, v[44:45]
	v_mov_b32_e32 v26, v85
	v_mov_b32_e32 v27, v81
	v_mov_b32_e32 v28, v83
	s_waitcnt lgkmcnt(0)
	v_lshl_add_u64 v[30:31], s[16:17], 0, v[30:31]
	v_lshl_add_u64 v[30:31], v[30:31], 0, v[0:1]
	v_lshl_add_u64 v[32:33], v[30:31], 0, s[34:35]
	v_add_co_u32_e32 v30, vcc, 0x9448000, v30
	v_mov_b32_e32 v29, v75
	s_nop 0
	v_addc_co_u32_e32 v31, vcc, 0, v31, vcc
	global_store_dwordx4 v[30:31], v[26:29], off
	s_nop 1
	v_mov_b32_e32 v26, v79
	v_mov_b32_e32 v27, v71
	v_mov_b32_e32 v28, v73
	v_mov_b32_e32 v29, v63
	global_store_dwordx4 v[32:33], v[26:29], off offset:16
.LBB0_281:
	s_or_b64 exec, exec, s[2:3]
	s_nop 0
	v_or_b32_e32 v26, 14, v42
	v_ashrrev_i32_e32 v27, 31, v26
	v_lshlrev_b64 v[98:99], 12, v[26:27]
	v_lshl_add_u64 v[26:27], v[50:51], 0, v[98:99]
	s_nop 0
	v_pk_mul_f32 v[88:89], v[52:53], v[88:89]
	v_mov_b32_e32 v96, v85
	v_pk_mul_f32 v[86:87], v[22:23], v[86:87]
	v_mov_b32_e32 v30, v81
	v_pk_mul_f32 v[76:77], v[38:39], v[76:77]
	v_mov_b32_e32 v94, v83
	v_pk_mul_f32 v[68:69], v[24:25], v[68:69]
	v_mov_b32_e32 v32, v75
	v_pk_mul_f32 v[66:67], v[40:41], v[66:67]
	v_mov_b32_e32 v92, v79
	v_pk_mul_f32 v[64:65], v[10:11], v[64:65]
	v_pk_mul_f32 v[60:61], v[56:57], v[60:61]
	v_mov_b32_e32 v90, v73
	v_pk_mul_f32 v[58:59], v[12:13], v[58:59]
	s_movk_i32 s2, 0xfee
	v_cmp_lt_u32_e32 vcc, s2, v111
	s_waitcnt vmcnt(0)
	v_mov_b64_e32 v[26:27], v[200:201]
	v_mov_b64_e32 v[28:29], v[202:203]
	v_lshlrev_b32_e32 v97, 16, v26
	v_and_b32_e32 v31, 0xffff0000, v26
	v_add_f32_e32 v26, v18, v88
	v_add_f32_e32 v26, v26, v89
	v_pk_mul_f32 v[88:89], v[48:49], v[96:97]
	v_lshlrev_b32_e32 v95, 16, v27
	v_add_f32_e32 v26, v26, v88
	v_add_f32_e32 v43, v26, v89
	v_add_f32_e32 v26, v19, v86
	v_add_f32_e32 v26, v26, v87
	v_pk_mul_f32 v[86:87], v[6:7], v[30:31]
	v_and_b32_e32 v33, 0xffff0000, v27
	v_add_f32_e32 v26, v26, v86
	v_add_f32_e32 v30, v26, v87
	v_add_f32_e32 v26, v20, v76
	v_add_f32_e32 v26, v26, v77
	v_pk_mul_f32 v[76:77], v[34:35], v[94:95]
	v_lshlrev_b32_e32 v93, 16, v28
	v_add_f32_e32 v26, v26, v76
	v_add_f32_e32 v76, v26, v77
	v_add_f32_e32 v26, v21, v68
	v_add_f32_e32 v26, v26, v69
	v_pk_mul_f32 v[68:69], v[8:9], v[32:33]
	v_and_b32_e32 v27, 0xffff0000, v28
	v_add_f32_e32 v26, v26, v68
	v_add_f32_e32 v32, v26, v69
	v_add_f32_e32 v26, v14, v66
	v_add_f32_e32 v26, v26, v67
	v_pk_mul_f32 v[66:67], v[36:37], v[92:93]
	v_lshlrev_b32_e32 v91, 16, v29
	v_add_f32_e32 v26, v26, v66
	v_add_f32_e32 v66, v26, v67
	v_add_f32_e32 v26, v15, v64
	v_add_f32_e32 v28, v26, v65
	v_mov_b32_e32 v26, v71
	v_pk_mul_f32 v[64:65], v[2:3], v[26:27]
	v_and_b32_e32 v29, 0xffff0000, v29
	v_add_f32_e32 v26, v28, v64
	v_add_f32_e32 v28, v16, v60
	v_add_f32_e32 v28, v28, v61
	v_pk_mul_f32 v[60:61], v[54:55], v[90:91]
	v_add_f32_e32 v26, v26, v65
	v_add_f32_e32 v28, v28, v60
	v_add_f32_e32 v61, v28, v61
	v_add_f32_e32 v28, v17, v58
	v_add_f32_e32 v60, v28, v59
	v_mov_b32_e32 v28, v63
	v_pk_mul_f32 v[58:59], v[4:5], v[28:29]
	v_lshl_add_u64 v[64:65], v[46:47], 0, v[98:99]
	v_add_f32_e32 v28, v60, v58
	v_add_f32_e32 v28, v28, v59
	v_cvt_pk_bf16_f32 v58, v43, v30
	v_cvt_pk_bf16_f32 v59, v76, v32
	v_cvt_pk_bf16_f32 v60, v66, v26
	v_cvt_pk_bf16_f32 v61, v61, v28
	global_store_dwordx4 v[64:65], v[58:61], off
	s_and_saveexec_b64 s[2:3], vcc
	s_cbranch_execz .LBB0_283
	s_load_dwordx2 s[16:17], s[0:1], 0xe0
	v_add_u32_e32 v58, 0xfffff011, v111
	v_mov_b32_e32 v59, v1
	v_lshl_add_u64 v[58:59], v[44:45], 0, v[58:59]
	v_lshlrev_b64 v[58:59], 13, v[58:59]
	s_waitcnt lgkmcnt(0)
	v_lshl_add_u64 v[58:59], s[16:17], 0, v[58:59]
	v_lshl_add_u64 v[58:59], v[58:59], 0, v[0:1]
	v_lshl_add_u64 v[60:61], v[58:59], 0, s[34:35]
	v_add_co_u32_e32 v58, vcc, 0x9448000, v58
	v_mov_b32_e32 v30, v97
	v_mov_b32_e32 v32, v95
	v_addc_co_u32_e32 v59, vcc, 0, v59, vcc
	v_mov_b32_e32 v26, v93
	v_mov_b32_e32 v28, v91
	global_store_dwordx4 v[58:59], v[30:33], off
	global_store_dwordx4 v[60:61], v[26:29], off offset:16
; __device__ __forceinline__ void unpack8(const v4u w, float (&f)[8]) { f[0] = bf_lo(w.x); f[1] = bf_hi(w.x); f[2] = bf_lo(w.y); f[3] = bf_hi(w.y); f[4] = bf_lo(w.z); f[5] = bf_hi(w.z); f[6] = bf_lo(w.w); f[7] = bf_hi(w.w); }
; __device__ __forceinline__ v4u pack8(const float (&f)[8]) { v4u w; w.x = cvt_pk_bf16(f[0], f[1]); w.y = cvt_pk_bf16(f[2], f[3]); w.z = cvt_pk_bf16(f[4], f[5]); w.w = cvt_pk_bf16(f[6], f[7]); return w; }
; __device__ __forceinline__ void lru_conv_own(const Frame& F, CArgs* A, int j, const bf16* U, bf16* UC) {
;     ...
; #pragma unroll
;         for (int r = 0; r < 16; ++r) { float x0[8], o[8]; unpack8(*(const v4u*)(U + (size_t)(m0 + r) * 2048 + c), x0);
; #pragma unroll
;             for (int e = 0; e < 8; ++e) o[e] = bias[e] + w[0][e] * x3[e] + w[1][e] * x2[e] + w[2][e] * x1[e] + w[3][e] * x0[e];
;             *(v4u*)(UC + (size_t)(m0 + r) * 2048 + c) = pack8(o);
;             if (t0 + r >= TSEQ - 3) store8f(A->out + O_LCP + ((size_t)(j * 2 + (m0 >> 12)) * 3 + (t0 + r - (TSEQ - 3))) * 2048 + c, x0);
; #pragma unroll
;             for (int e = 0; e < 8; ++e) { x3[e] = x2[e]; x2[e] = x1[e]; x1[e] = x0[e]; } }
;     }
.LBB0_283:
	s_or_b64 exec, exec, s[2:3]
	v_or_b32_e32 v42, 15, v42
	v_ashrrev_i32_e32 v43, 31, v42
	v_lshlrev_b64 v[42:43], 12, v[42:43]
	v_lshl_add_u64 v[50:51], v[50:51], 0, v[42:43]
	s_nop 0
	v_pk_mul_f32 v[50:51], v[52:53], v[84:85]
	v_pk_mul_f32 v[52:53], v[22:23], v[80:81]
	v_pk_mul_f32 v[40:41], v[40:41], v[78:79]
	v_pk_mul_f32 v[62:63], v[12:13], v[62:63]
	v_add_f32_e32 v13, v19, v52
	v_pk_mul_f32 v[38:39], v[38:39], v[82:83]
	v_pk_mul_f32 v[64:65], v[24:25], v[74:75]
	v_pk_mul_f32 v[66:67], v[10:11], v[70:71]
	v_pk_mul_f32 v[56:57], v[56:57], v[72:73]
	v_mov_b32_e32 v12, v29
	v_add_f32_e32 v11, v18, v50
	v_add_f32_e32 v14, v14, v40
	v_add_f32_e32 v17, v17, v62
	v_add_f32_e32 v40, v13, v53
	v_mov_b32_e32 v26, v97
	v_mov_b32_e32 v22, v31
	v_mov_b32_e32 v28, v95
	v_mov_b32_e32 v24, v33
	v_mov_b32_e32 v30, v93
	v_mov_b32_e32 v10, v27
	v_mov_b32_e32 v32, v91
	v_add_f32_e32 v18, v20, v38
	v_add_f32_e32 v19, v21, v64
	v_add_f32_e32 v15, v15, v66
	v_add_f32_e32 v16, v16, v56
	v_add_f32_e32 v38, v11, v51
	v_add_f32_e32 v53, v17, v63
	v_add_f32_e32 v39, v18, v39
	v_add_f32_e32 v50, v19, v65
	v_add_f32_e32 v41, v14, v41
	v_add_f32_e32 v51, v15, v67
	v_add_f32_e32 v52, v16, v57
	s_movk_i32 s2, 0xfed
	v_lshl_add_u64 v[14:15], v[46:47], 0, v[42:43]
	v_cmp_lt_u32_e32 vcc, s2, v111
	s_waitcnt vmcnt(0)
	v_mov_b64_e32 v[58:59], v[204:205]
	v_mov_b64_e32 v[60:61], v[206:207]
	v_and_b32_e32 v13, 0xffff0000, v61
	v_lshlrev_b32_e32 v27, 16, v58
	v_and_b32_e32 v23, 0xffff0000, v58
	v_lshlrev_b32_e32 v29, 16, v59
	v_and_b32_e32 v25, 0xffff0000, v59
	v_lshlrev_b32_e32 v31, 16, v60
	v_and_b32_e32 v11, 0xffff0000, v60
	v_lshlrev_b32_e32 v33, 16, v61
	v_pk_mul_f32 v[4:5], v[4:5], v[12:13]
	v_pk_mul_f32 v[16:17], v[48:49], v[26:27]
	v_pk_mul_f32 v[6:7], v[6:7], v[22:23]
	v_pk_mul_f32 v[18:19], v[34:35], v[28:29]
	v_pk_mul_f32 v[8:9], v[8:9], v[24:25]
	v_pk_mul_f32 v[20:21], v[36:37], v[30:31]
	v_pk_mul_f32 v[2:3], v[2:3], v[10:11]
	v_pk_mul_f32 v[34:35], v[54:55], v[32:33]
	v_add_f32_e32 v4, v53, v4
	v_add_f32_e32 v10, v38, v16
	v_add_f32_e32 v6, v40, v6
	v_add_f32_e32 v12, v39, v18
	v_add_f32_e32 v8, v50, v8
	v_add_f32_e32 v16, v41, v20
	v_add_f32_e32 v2, v51, v2
	v_add_f32_e32 v18, v52, v34
	v_add_f32_e32 v5, v4, v5
	v_add_f32_e32 v10, v10, v17
	v_add_f32_e32 v6, v6, v7
	v_add_f32_e32 v7, v12, v19
	v_add_f32_e32 v8, v8, v9
	v_add_f32_e32 v9, v16, v21
	v_add_f32_e32 v12, v2, v3
	v_add_f32_e32 v16, v18, v35
	v_cvt_pk_bf16_f32 v2, v10, v6
	v_cvt_pk_bf16_f32 v3, v7, v8
	v_cvt_pk_bf16_f32 v4, v9, v12
	v_cvt_pk_bf16_f32 v5, v16, v5
	global_store_dwordx4 v[14:15], v[2:5], off
	s_and_saveexec_b64 s[2:3], vcc
	s_cbranch_execz .LBB0_276
	s_load_dwordx2 s[16:17], s[0:1], 0xe0
	v_add_u32_e32 v2, 0xfffff012, v111
	v_mov_b32_e32 v3, v1
	v_lshl_add_u64 v[2:3], v[44:45], 0, v[2:3]
	v_lshlrev_b64 v[2:3], 13, v[2:3]
	s_waitcnt lgkmcnt(0)
	v_lshl_add_u64 v[2:3], s[16:17], 0, v[2:3]
	v_lshl_add_u64 v[2:3], v[2:3], 0, v[0:1]
	v_lshl_add_u64 v[4:5], v[2:3], 0, s[34:35]
	v_add_co_u32_e32 v2, vcc, 0x9448000, v2
	v_mov_b32_e32 v22, v27
	v_mov_b32_e32 v24, v29
	v_addc_co_u32_e32 v3, vcc, 0, v3, vcc
	v_mov_b32_e32 v10, v31
	v_mov_b32_e32 v12, v33
	global_store_dwordx4 v[2:3], v[22:25], off
	global_store_dwordx4 v[4:5], v[10:13], off offset:16
	s_branch .LBB0_276

; __device__ __forceinline__ void unpack8(const v4u w, float (&f)[8]) { f[0] = bf_lo(w.x); f[1] = bf_hi(w.x); f[2] = bf_lo(w.y); f[3] = bf_hi(w.y); f[4] = bf_lo(w.z); f[5] = bf_hi(w.z); f[6] = bf_lo(w.w); f[7] = bf_hi(w.w); }
; __device__ __forceinline__ void lru_conv_own(const Frame& F, CArgs* A, int j, const bf16* U, bf16* UC) {
;     ...
;         for (int q2 = 0; q2 < 2; ++q2) { const int q = F.tid + 512 * q2, row = q >> 5, c = hd * 256 + (q & 31) * 8, b = row >> 2, t = row & 3; const int m = MP + row;
;             float acc[8], x0[8] = {0.f, 0.f, 0.f, 0.f, 0.f, 0.f, 0.f, 0.f}; load8f(cb + c, acc);
; #pragma unroll
;             for (int k = 0; k < 4; ++k) { const int d = 3 - k; float w[8], x[8]; load8f(cw + (size_t)k * 2048 + c, w);
;                 if (t >= d) unpack8(*(const v4u*)(U + (size_t)(m - d) * 2048 + c), x); else load8f(st + ((size_t)b * 3 + (t + 3 - d)) * 2048 + c, x);
.LBB0_289:
	s_or_saveexec_b64 s[14:15], s[14:15]
	v_lshlrev_b32_e32 v102, 1, v2
	v_mov_b32_e32 v103, v1
	v_lshl_add_u64 v[104:105], s[18:19], 0, v[102:103]
	s_xor_b64 exec, exec, s[14:15]
	s_cbranch_execz .LBB0_291
	v_lshl_add_u64 v[2:3], v[104:105], 0, v[70:71]
	global_load_dwordx4 v[120:123], v[2:3], off
.LBB0_291:
	s_or_b64 exec, exec, s[14:15]
	v_lshl_add_u64 v[114:115], s[26:27], 0, v[0:1]
	v_add_co_u32_e32 v2, vcc, 0x2000, v114
	s_mov_b64 s[14:15], 0x2000
	s_nop 0
	v_addc_co_u32_e32 v3, vcc, 0, v115, vcc
	v_lshl_add_u64 v[110:111], v[114:115], 0, s[14:15]
	global_load_dwordx4 v[54:57], v[2:3], off
	global_load_dwordx4 v[50:53], v[110:111], off offset:16
	s_and_saveexec_b64 s[14:15], s[40:41]
	s_xor_b64 s[14:15], exec, s[14:15]
	s_cbranch_execz .LBB0_293
	v_lshl_add_u64 v[2:3], v[104:105], 0, v[72:73]
	global_load_dwordx4 v[124:127], v[2:3], off

; __device__ __forceinline__ void unpack8(const v4u w, float (&f)[8]) { f[0] = bf_lo(w.x); f[1] = bf_hi(w.x); f[2] = bf_lo(w.y); f[3] = bf_hi(w.y); f[4] = bf_lo(w.z); f[5] = bf_hi(w.z); f[6] = bf_lo(w.w); f[7] = bf_hi(w.w); }
; __device__ __forceinline__ v4u pack8(const float (&f)[8]) { v4u w; w.x = cvt_pk_bf16(f[0], f[1]); w.y = cvt_pk_bf16(f[2], f[3]); w.z = cvt_pk_bf16(f[4], f[5]); w.w = cvt_pk_bf16(f[6], f[7]); return w; }
; __device__ __forceinline__ void lru_conv_own(const Frame& F, CArgs* A, int j, const bf16* U, bf16* UC) {
;     ...
;         for (int q2 = 0; q2 < 2; ++q2) { const int q = F.tid + 512 * q2, row = q >> 5, c = hd * 256 + (q & 31) * 8, b = row >> 2, t = row & 3; const int m = MP + row;
;             float acc[8], x0[8] = {0.f, 0.f, 0.f, 0.f, 0.f, 0.f, 0.f, 0.f}; load8f(cb + c, acc);
; #pragma unroll
;             for (int k = 0; k < 4; ++k) { const int d = 3 - k; float w[8], x[8]; load8f(cw + (size_t)k * 2048 + c, w);
;                 if (t >= d) unpack8(*(const v4u*)(U + (size_t)(m - d) * 2048 + c), x); else load8f(st + ((size_t)b * 3 + (t + 3 - d)) * 2048 + c, x);
; #pragma unroll
;                 for (int e = 0; e < 8; ++e) acc[e] += w[e] * x[e];
;                 if (k == 3) {
; #pragma unroll
;                     for (int e = 0; e < 8; ++e) x0[e] = x[e]; } }
;             *(v4u*)(UC + (size_t)m * 2048 + c) = pack8(acc);
;             if (t >= 1) store8f(A->out + O_LCS + ((size_t)(j * SB + b) * 3 + (t - 1)) * 2048 + c, x0); }
.LBB0_295:
	s_or_b64 exec, exec, s[14:15]
	v_add_co_u32_e32 v2, vcc, 0x4000, v114
	s_mov_b64 s[14:15], 0x4000
	s_nop 0
	v_addc_co_u32_e32 v3, vcc, 0, v115, vcc
	v_lshl_add_u64 v[112:113], v[114:115], 0, s[14:15]
	global_load_dwordx4 v[30:33], v[2:3], off
	global_load_dwordx4 v[26:29], v[112:113], off offset:16
	s_and_saveexec_b64 s[14:15], s[10:11]
	s_xor_b64 s[14:15], exec, s[14:15]
	s_cbranch_execz .LBB0_297
	v_lshl_add_u64 v[2:3], v[104:105], 0, v[76:77]
	global_load_dwordx4 v[128:131], v[2:3], off
.LBB0_297:
	s_andn2_saveexec_b64 s[14:15], s[14:15]
	s_cbranch_execz .LBB0_299
	v_lshl_add_u64 v[2:3], v[106:107], 0, v[78:79]
	v_add_co_u32_e32 v4, vcc, 0x4000, v2
	s_mov_b64 s[34:35], 0x4000
	s_nop 0
	v_addc_co_u32_e32 v5, vcc, 0, v3, vcc
	v_lshl_add_u64 v[2:3], v[2:3], 0, s[34:35]
	global_load_dwordx4 v[10:13], v[4:5], off
	global_load_dwordx4 v[132:135], v[2:3], off offset:16
.LBB0_299:
	s_or_b64 exec, exec, s[14:15]
	s_waitcnt vmcnt(0)
	s_mov_b64 s[14:15], exec
	s_andn2_b64 exec, s[14:15], s[38:39]
	v_lshlrev_b32_e32 v42, 16, v120
	v_and_b32_e32 v43, 0xffff0000, v120
	v_lshlrev_b32_e32 v44, 16, v121
	v_and_b32_e32 v45, 0xffff0000, v121
	v_lshlrev_b32_e32 v46, 16, v122
	v_and_b32_e32 v47, 0xffff0000, v122
	v_lshlrev_b32_e32 v48, 16, v123
	v_and_b32_e32 v49, 0xffff0000, v123
	s_and_b64 exec, s[14:15], s[40:41]
	v_lshlrev_b32_e32 v58, 16, v124
	v_and_b32_e32 v59, 0xffff0000, v124
	v_lshlrev_b32_e32 v60, 16, v125
	v_and_b32_e32 v61, 0xffff0000, v125
	v_lshlrev_b32_e32 v62, 16, v126
	v_and_b32_e32 v63, 0xffff0000, v126
	v_lshlrev_b32_e32 v64, 16, v127
	v_and_b32_e32 v65, 0xffff0000, v127
	s_and_b64 exec, s[14:15], s[10:11]
	v_lshlrev_b32_e32 v10, 16, v128
	v_and_b32_e32 v6, 0xffff0000, v128
	v_lshlrev_b32_e32 v12, 16, v129
	v_and_b32_e32 v8, 0xffff0000, v129
	v_lshlrev_b32_e32 v2, 16, v130
	v_and_b32_e32 v14, 0xffff0000, v130
	v_lshlrev_b32_e32 v4, 16, v131
	v_and_b32_e32 v16, 0xffff0000, v131
	s_andn2_b64 exec, s[14:15], s[10:11]
	v_mov_b32_e32 v6, v11
	v_mov_b32_e32 v8, v13
	v_mov_b32_e32 v2, v132
	v_mov_b32_e32 v14, v133
	v_mov_b32_e32 v4, v134
	v_mov_b32_e32 v16, v135
	s_mov_b64 exec, s[14:15]
	v_fma_f32 v46, v34, v46, v18
	v_add_co_u32_e32 v18, vcc, s69, v114
	v_fma_f32 v47, v35, v47, v19
	s_mov_b64 s[14:15], 0x6000
	v_addc_co_u32_e32 v19, vcc, 0, v115, vcc
	v_fma_f32 v22, v38, v42, v22
	v_fma_f32 v23, v39, v43, v23
	v_fma_f32 v24, v40, v44, v24
	v_fmac_f32_e32 v25, v41, v45
	v_fma_f32 v20, v36, v48, v20
	v_fmac_f32_e32 v21, v37, v49
	v_lshl_add_u64 v[108:109], v[114:115], 0, s[14:15]
	global_load_dwordx4 v[38:41], v[18:19], off
	global_load_dwordx4 v[34:37], v[108:109], off offset:16
	v_lshl_add_u64 v[18:19], v[104:105], 0, v[66:67]
	global_load_dwordx4 v[42:45], v[18:19], off
	s_waitcnt vmcnt(4)
	v_mov_b32_e32 v18, v30
	v_fmac_f32_e32 v22, v54, v58
	v_fmac_f32_e32 v23, v55, v59
	v_fmac_f32_e32 v24, v56, v60
	v_fmac_f32_e32 v25, v57, v61
	v_fmac_f32_e32 v46, v50, v62
	v_fmac_f32_e32 v47, v51, v63
	v_fmac_f32_e32 v20, v52, v64
	v_fmac_f32_e32 v21, v53, v65
	v_mov_b32_e32 v103, v1
	s_waitcnt vmcnt(2)
	v_mov_b32_e32 v19, v38
	v_mov_b32_e32 v38, v31
	s_waitcnt vmcnt(0)
	v_lshlrev_b32_e32 v11, 16, v42
	v_pk_mul_f32 v[18:19], v[18:19], v[10:11]
	v_and_b32_e32 v7, 0xffff0000, v42
	v_add_f32_e32 v10, v22, v18
	v_add_f32_e32 v10, v10, v19
	v_pk_mul_f32 v[18:19], v[38:39], v[6:7]
	v_lshlrev_b32_e32 v13, 16, v43
	v_add_f32_e32 v6, v23, v18
	v_add_f32_e32 v6, v6, v19
	v_mov_b32_e32 v18, v32
	v_mov_b32_e32 v19, v40
	v_pk_mul_f32 v[18:19], v[18:19], v[12:13]
	v_and_b32_e32 v9, 0xffff0000, v43
	v_add_f32_e32 v12, v24, v18
	v_mov_b32_e32 v40, v33
	v_add_f32_e32 v12, v12, v19
	v_pk_mul_f32 v[18:19], v[40:41], v[8:9]
	v_lshlrev_b32_e32 v3, 16, v44
	v_add_f32_e32 v8, v25, v18
	v_add_f32_e32 v8, v8, v19
	v_mov_b32_e32 v18, v26
	v_mov_b32_e32 v19, v34
	v_pk_mul_f32 v[18:19], v[18:19], v[2:3]
	v_and_b32_e32 v15, 0xffff0000, v44
	v_add_f32_e32 v2, v46, v18
	v_mov_b32_e32 v34, v27
	v_add_f32_e32 v2, v2, v19
	v_pk_mul_f32 v[18:19], v[34:35], v[14:15]
	v_lshlrev_b32_e32 v5, 16, v45
	v_add_f32_e32 v14, v47, v18
	v_add_f32_e32 v14, v14, v19
	v_mov_b32_e32 v18, v28
	v_mov_b32_e32 v19, v36
	v_pk_mul_f32 v[18:19], v[18:19], v[4:5]
	v_and_b32_e32 v17, 0xffff0000, v45
	v_add_f32_e32 v4, v20, v18
	v_mov_b32_e32 v36, v29
	v_add_f32_e32 v4, v4, v19
	v_pk_mul_f32 v[18:19], v[36:37], v[16:17]
	v_lshl_add_u64 v[22:23], v[80:81], 0, v[102:103]
	v_add_f32_e32 v16, v21, v18
	v_add_f32_e32 v16, v16, v19
	v_cvt_pk_bf16_f32 v18, v10, v6
	v_cvt_pk_bf16_f32 v19, v12, v8
	v_cvt_pk_bf16_f32 v20, v2, v14
	v_cvt_pk_bf16_f32 v21, v4, v16
	global_store_dwordx4 v[22:23], v[18:21], off
	s_and_saveexec_b64 s[14:15], s[10:11]
	s_cbranch_execz .LBB0_301
	s_load_dwordx2 s[34:35], s[0:1], 0xe0
	v_mov_b32_e32 v6, v11
	v_mov_b32_e32 v8, v13
	v_mov_b32_e32 v14, v3
	v_mov_b32_e32 v16, v5
	s_waitcnt lgkmcnt(0)
	v_lshl_add_u64 v[10:11], s[34:35], 0, v[82:83]
	v_lshl_add_u64 v[10:11], v[10:11], 0, v[0:1]
	s_mov_b64 s[34:35], 0x96c0000
	v_lshl_add_u64 v[12:13], v[10:11], 0, s[34:35]
	v_add_co_u32_e32 v10, vcc, 0x96c0000, v10
	global_store_dwordx4 v[12:13], v[14:17], off offset:16
	s_nop 0
	v_addc_co_u32_e32 v11, vcc, 0, v11, vcc
	global_store_dwordx4 v[10:11], v[6:9], off

; __device__ __forceinline__ void unpack8(const v4u w, float (&f)[8]) { f[0] = bf_lo(w.x); f[1] = bf_hi(w.x); f[2] = bf_lo(w.y); f[3] = bf_hi(w.y); f[4] = bf_lo(w.z); f[5] = bf_hi(w.z); f[6] = bf_lo(w.w); f[7] = bf_hi(w.w); }
; __device__ __forceinline__ void lru_conv_own(const Frame& F, CArgs* A, int j, const bf16* U, bf16* UC) {
;     ...
;         for (int q2 = 0; q2 < 2; ++q2) { const int q = F.tid + 512 * q2, row = q >> 5, c = hd * 256 + (q & 31) * 8, b = row >> 2, t = row & 3; const int m = MP + row;
;             float acc[8], x0[8] = {0.f, 0.f, 0.f, 0.f, 0.f, 0.f, 0.f, 0.f}; load8f(cb + c, acc);
; #pragma unroll
;             for (int k = 0; k < 4; ++k) { const int d = 3 - k; float w[8], x[8]; load8f(cw + (size_t)k * 2048 + c, w);
;                 if (t >= d) unpack8(*(const v4u*)(U + (size_t)(m - d) * 2048 + c), x); else load8f(st + ((size_t)b * 3 + (t + 3 - d)) * 2048 + c, x);
.LBB0_303:
	s_andn2_saveexec_b64 s[14:15], s[14:15]
	s_cbranch_execz .LBB0_305
	v_lshl_add_u64 v[2:3], v[104:105], 0, v[86:87]
	global_load_dwordx4 v[120:123], v[2:3], off
.LBB0_305:
	s_or_b64 exec, exec, s[14:15]
	global_load_dwordx4 v[50:53], v[110:111], off offset:16
	global_load_dwordx4 v[54:57], v[110:111], off
	s_and_saveexec_b64 s[14:15], s[44:45]
	s_xor_b64 s[14:15], exec, s[14:15]
	s_cbranch_execz .LBB0_307
	v_lshl_add_u64 v[2:3], v[104:105], 0, v[88:89]
	global_load_dwordx4 v[124:127], v[2:3], off

; __device__ __forceinline__ void unpack8(const v4u w, float (&f)[8]) { f[0] = bf_lo(w.x); f[1] = bf_hi(w.x); f[2] = bf_lo(w.y); f[3] = bf_hi(w.y); f[4] = bf_lo(w.z); f[5] = bf_hi(w.z); f[6] = bf_lo(w.w); f[7] = bf_hi(w.w); }
; __device__ __forceinline__ v4u pack8(const float (&f)[8]) { v4u w; w.x = cvt_pk_bf16(f[0], f[1]); w.y = cvt_pk_bf16(f[2], f[3]); w.z = cvt_pk_bf16(f[4], f[5]); w.w = cvt_pk_bf16(f[6], f[7]); return w; }
; __device__ __forceinline__ void lru_conv_own(const Frame& F, CArgs* A, int j, const bf16* U, bf16* UC) {
;     ...
;         for (int q2 = 0; q2 < 2; ++q2) { const int q = F.tid + 512 * q2, row = q >> 5, c = hd * 256 + (q & 31) * 8, b = row >> 2, t = row & 3; const int m = MP + row;
;             float acc[8], x0[8] = {0.f, 0.f, 0.f, 0.f, 0.f, 0.f, 0.f, 0.f}; load8f(cb + c, acc);
; #pragma unroll
;             for (int k = 0; k < 4; ++k) { const int d = 3 - k; float w[8], x[8]; load8f(cw + (size_t)k * 2048 + c, w);
;                 if (t >= d) unpack8(*(const v4u*)(U + (size_t)(m - d) * 2048 + c), x); else load8f(st + ((size_t)b * 3 + (t + 3 - d)) * 2048 + c, x);
; #pragma unroll
;                 for (int e = 0; e < 8; ++e) acc[e] += w[e] * x[e];
;                 if (k == 3) {
; #pragma unroll
;                     for (int e = 0; e < 8; ++e) x0[e] = x[e]; } }
;             *(v4u*)(UC + (size_t)m * 2048 + c) = pack8(acc);
;             if (t >= 1) store8f(A->out + O_LCS + ((size_t)(j * SB + b) * 3 + (t - 1)) * 2048 + c, x0); }
.LBB0_309:
	s_or_b64 exec, exec, s[14:15]
	global_load_dwordx4 v[26:29], v[112:113], off offset:16
	global_load_dwordx4 v[30:33], v[112:113], off
	s_and_saveexec_b64 s[14:15], s[12:13]
	s_xor_b64 s[14:15], exec, s[14:15]
	s_cbranch_execz .LBB0_311
	v_lshl_add_u64 v[2:3], v[104:105], 0, v[92:93]
	global_load_dwordx4 v[128:131], v[2:3], off
.LBB0_311:
	s_andn2_saveexec_b64 s[14:15], s[14:15]
	s_cbranch_execz .LBB0_313
	v_lshl_add_u64 v[2:3], v[106:107], 0, v[94:95]
	v_add_co_u32_e32 v4, vcc, 0x4000, v2
	s_mov_b64 s[34:35], 0x4000
	s_nop 0
	v_addc_co_u32_e32 v5, vcc, 0, v3, vcc
	v_lshl_add_u64 v[2:3], v[2:3], 0, s[34:35]
	global_load_dwordx4 v[10:13], v[4:5], off
	global_load_dwordx4 v[132:135], v[2:3], off offset:16
.LBB0_313:
	s_or_b64 exec, exec, s[14:15]
	s_waitcnt vmcnt(0)
	s_mov_b64 s[14:15], exec
	s_andn2_b64 exec, s[14:15], s[42:43]
	v_lshlrev_b32_e32 v42, 16, v120
	v_and_b32_e32 v43, 0xffff0000, v120
	v_lshlrev_b32_e32 v44, 16, v121
	v_and_b32_e32 v45, 0xffff0000, v121
	v_lshlrev_b32_e32 v46, 16, v122
	v_and_b32_e32 v47, 0xffff0000, v122
	v_lshlrev_b32_e32 v48, 16, v123
	v_and_b32_e32 v49, 0xffff0000, v123
	s_and_b64 exec, s[14:15], s[44:45]
	v_lshlrev_b32_e32 v58, 16, v124
	v_and_b32_e32 v59, 0xffff0000, v124
	v_lshlrev_b32_e32 v60, 16, v125
	v_and_b32_e32 v61, 0xffff0000, v125
	v_lshlrev_b32_e32 v62, 16, v126
	v_and_b32_e32 v63, 0xffff0000, v126
	v_lshlrev_b32_e32 v64, 16, v127
	v_and_b32_e32 v65, 0xffff0000, v127
	s_and_b64 exec, s[14:15], s[12:13]
	v_lshlrev_b32_e32 v10, 16, v128
	v_and_b32_e32 v6, 0xffff0000, v128
	v_lshlrev_b32_e32 v12, 16, v129
	v_and_b32_e32 v8, 0xffff0000, v129
	v_lshlrev_b32_e32 v2, 16, v130
	v_and_b32_e32 v14, 0xffff0000, v130
	v_lshlrev_b32_e32 v4, 16, v131
	v_and_b32_e32 v16, 0xffff0000, v131
	s_andn2_b64 exec, s[14:15], s[12:13]
	v_mov_b32_e32 v6, v11
	v_mov_b32_e32 v8, v13
	v_mov_b32_e32 v2, v132
	v_mov_b32_e32 v14, v133
	v_mov_b32_e32 v4, v134
	v_mov_b32_e32 v16, v135
	s_mov_b64 exec, s[14:15]
	v_fma_f32 v46, v34, v46, v18
	v_fma_f32 v47, v35, v47, v19
	v_lshl_add_u64 v[18:19], v[104:105], 0, v[96:97]
	v_fma_f32 v22, v38, v42, v22
	v_fma_f32 v23, v39, v43, v23
	v_fma_f32 v24, v40, v44, v24
	v_fmac_f32_e32 v25, v41, v45
	v_fma_f32 v20, v36, v48, v20
	v_fmac_f32_e32 v21, v37, v49
	global_load_dwordx4 v[34:37], v[108:109], off offset:16
	global_load_dwordx4 v[38:41], v[108:109], off
	global_load_dwordx4 v[42:45], v[18:19], off
	s_waitcnt vmcnt(3)
	v_mov_b32_e32 v18, v30
	v_fmac_f32_e32 v22, v54, v58
	v_fmac_f32_e32 v23, v55, v59
	v_fmac_f32_e32 v24, v56, v60
	v_fmac_f32_e32 v25, v57, v61
	v_fmac_f32_e32 v46, v50, v62
	v_fmac_f32_e32 v47, v51, v63
	v_fmac_f32_e32 v20, v52, v64
	v_fmac_f32_e32 v21, v53, v65
	v_mov_b32_e32 v103, v1
	s_waitcnt vmcnt(1)
	v_mov_b32_e32 v19, v38
	s_waitcnt vmcnt(0)
	v_lshlrev_b32_e32 v11, 16, v42
	v_pk_mul_f32 v[18:19], v[18:19], v[10:11]
	v_and_b32_e32 v7, 0xffff0000, v42
	v_add_f32_e32 v10, v22, v18
	v_mov_b32_e32 v38, v31
	v_add_f32_e32 v10, v10, v19
	v_pk_mul_f32 v[18:19], v[38:39], v[6:7]
	v_lshlrev_b32_e32 v13, 16, v43
	v_add_f32_e32 v6, v23, v18
	v_add_f32_e32 v6, v6, v19
	v_mov_b32_e32 v18, v32
	v_mov_b32_e32 v19, v40
	v_pk_mul_f32 v[18:19], v[18:19], v[12:13]
	v_and_b32_e32 v9, 0xffff0000, v43
	v_add_f32_e32 v12, v24, v18
	v_mov_b32_e32 v40, v33
	v_add_f32_e32 v12, v12, v19
	v_pk_mul_f32 v[18:19], v[40:41], v[8:9]
	v_lshlrev_b32_e32 v3, 16, v44
	v_add_f32_e32 v8, v25, v18
	v_add_f32_e32 v8, v8, v19
	v_mov_b32_e32 v18, v26
	v_mov_b32_e32 v19, v34
	v_pk_mul_f32 v[18:19], v[18:19], v[2:3]
	v_and_b32_e32 v15, 0xffff0000, v44
	v_add_f32_e32 v2, v46, v18
	v_mov_b32_e32 v34, v27
	v_add_f32_e32 v2, v2, v19
	v_pk_mul_f32 v[18:19], v[34:35], v[14:15]
	v_lshlrev_b32_e32 v5, 16, v45
	v_add_f32_e32 v14, v47, v18
	v_add_f32_e32 v14, v14, v19
	v_mov_b32_e32 v18, v28
	v_mov_b32_e32 v19, v36
	v_pk_mul_f32 v[18:19], v[18:19], v[4:5]
	v_and_b32_e32 v17, 0xffff0000, v45
	v_add_f32_e32 v4, v20, v18
	v_mov_b32_e32 v36, v29
	v_add_f32_e32 v4, v4, v19
	v_pk_mul_f32 v[18:19], v[36:37], v[16:17]
	v_lshl_add_u64 v[22:23], v[98:99], 0, v[102:103]
	v_add_f32_e32 v16, v21, v18
	v_add_f32_e32 v16, v16, v19
	v_cvt_pk_bf16_f32 v18, v10, v6
	v_cvt_pk_bf16_f32 v19, v12, v8
	v_cvt_pk_bf16_f32 v20, v2, v14
	v_cvt_pk_bf16_f32 v21, v4, v16
	global_store_dwordx4 v[22:23], v[18:21], off
	s_and_saveexec_b64 s[14:15], s[12:13]
	s_cbranch_execz .LBB0_286
	s_load_dwordx2 s[34:35], s[0:1], 0xe0
	v_mov_b32_e32 v6, v11
	v_mov_b32_e32 v8, v13
	v_mov_b32_e32 v14, v3
	v_mov_b32_e32 v16, v5
	s_waitcnt lgkmcnt(0)
	v_lshl_add_u64 v[10:11], s[34:35], 0, v[100:101]
	v_lshl_add_u64 v[10:11], v[10:11], 0, v[0:1]
	s_mov_b64 s[34:35], 0x96c0000
	v_lshl_add_u64 v[12:13], v[10:11], 0, s[34:35]
	v_add_co_u32_e32 v10, vcc, 0x96c0000, v10
	global_store_dwordx4 v[12:13], v[14:17], off offset:16
	s_nop 0
	v_addc_co_u32_e32 v11, vcc, 0, v11, vcc
	global_store_dwordx4 v[10:11], v[6:9], off
	s_branch .LBB0_286
